# combined: adaLN GEMV ring-of-4 prefetch + down/w_out tile groups 4x8 (ACT streamed once) + pre-pass 16-byte write-through stores via LDS staging
# speedup vs baseline: 1.0042x; 1.0042x over previous
; __device__ __forceinline__ float siluf_(float x) { return x * sigmoidf_(x); }
; __device__ __forceinline__ void phase_prologue(const In& in, unsigned char* ws, LAS unsigned char* lds, int tid, int wave, int lane) {
;     ...
;     for (int i = tid; i < NBATCH * D; i += 512) { const int b = i >> 11, k = i & 2047; condT[k * 8 + b] = siluf_(in.c[i]); }
;     __syncthreads();
;     float* mod = (float*)(ws + WS_MOD);
;     if (wave < 3) {
;         const int id = (int)blockIdx.x + 256 * wave;
;         if (id < 576) {
;             const int l = id / 288, cg = id % 288, col = cg * 64 + lane;
;             const float* W = in.w_ada + (size_t)l * D * NMOD + col;
;             float acc[8];
; #pragma unroll
;             for (int b = 0; b < 8; ++b) acc[b] = 0.f;
;             for (int k0 = 0; k0 < D; k0 += 16) {
;                 float w[16];
; #pragma unroll
;                 for (int j = 0; j < 16; ++j) w[j] = W[(size_t)(k0 + j) * NMOD];
.LBB0_11:
	global_load_dword v6, v[2:3], off
	v_lshrrev_b32_e32 v8, 9, v5
	v_add_u32_e32 v9, 0x200, v5
	v_cmp_lt_u32_e32 vcc, s6, v5
	v_and_b32_e32 v7, 0x3ff8, v4
	v_lshlrev_b32_e32 v7, 2, v7
	v_and_b32_e32 v8, 0x7ffffc, v8
	v_add_u32_e32 v4, 0x1000, v4
	v_lshl_add_u64 v[2:3], v[2:3], 0, s[4:5]
	s_or_b64 s[0:1], vcc, s[0:1]
	v_add3_u32 v7, 0, v7, v8
	s_waitcnt vmcnt(0)
	v_mul_f32_e32 v10, 0xbfb8aa3b, v6
	v_exp_f32_e32 v10, v10
	s_nop 0
	v_add_f32_e32 v5, 1.0, v10
	v_rcp_f32_e32 v10, v5
	v_mov_b32_e32 v5, v9
	v_mul_f32_e32 v6, v6, v10
	ds_write_b32 v7, v6
	s_andn2_b64 exec, exec, s[0:1]
	s_cbranch_execnz .LBB0_11
	s_or_b64 exec, exec, s[0:1]
	s_lshr_b32 s8, s9, 6
	s_cmpk_gt_u32 s9, 0xbf
	s_cselect_b64 s[0:1], -1, 0
	s_lshl_b32 s10, s8, 8
	s_add_i32 s10, s10, s67
	s_cmpk_gt_i32 s10, 0x23f
	s_cselect_b64 s[4:5], -1, 0
	s_or_b64 s[0:1], s[0:1], s[4:5]
	v_and_b32_e32 v16, 63, v0
	s_and_b64 vcc, exec, s[0:1]
	s_waitcnt lgkmcnt(0)
	s_barrier
	s_cbranch_vccnz .LBB0_16
	s_mul_hi_i32 s0, s10, 0x38e38e39
	s_lshr_b32 s1, s0, 31
	s_ashr_i32 s0, s0, 6
	s_add_i32 s9, s0, s1
	v_readlane_b32 s36, v252, 19
	s_mul_i32 s0, s9, 0x9000000
	v_lshl_or_b32 v2, s10, 6, v16
	s_mul_i32 s4, s9, 0x4800
	v_readlane_b32 s40, v252, 23
	s_mul_hi_i32 s1, s9, 0x9000000
	v_subrev_u32_e32 v2, s4, v2
	v_readlane_b32 s41, v252, 24
	s_add_u32 s0, s40, s0
	v_ashrrev_i32_e32 v3, 31, v2
	s_addc_u32 s1, s41, s1
	v_lshl_add_u64 v[2:3], v[2:3], 2, s[0:1]
	s_mov_b64 s[0:1], 0x90000
	v_mov_b32_e32 v4, 0
	v_lshl_add_u64 v[2:3], v[2:3], 0, s[0:1]
	s_mov_b32 s11, -16
	s_mov_b32 s12, 0
	s_mov_b64 s[6:7], 0x120000
	v_mov_b32_e32 v5, v4
	v_mov_b32_e32 v10, v4
	v_mov_b32_e32 v11, v4
	v_mov_b32_e32 v8, v4
	v_mov_b32_e32 v9, v4
	v_mov_b32_e32 v6, v4
	v_mov_b32_e32 v7, v4
	v_readlane_b32 s37, v252, 20
	v_readlane_b32 s38, v252, 21
	v_readlane_b32 s39, v252, 22
	v_readlane_b32 s42, v252, 25
	v_readlane_b32 s43, v252, 26
	v_readlane_b32 s44, v252, 27
	v_readlane_b32 s45, v252, 28
	v_readlane_b32 s46, v252, 29
	v_readlane_b32 s47, v252, 30
	v_readlane_b32 s48, v252, 31
	v_readlane_b32 s49, v252, 32
	v_readlane_b32 s50, v252, 33
	v_readlane_b32 s51, v252, 34
	v_readfirstlane_b32 s0, v2
	v_readfirstlane_b32 s1, v3
	v_lshlrev_b32_e32 v12, 2, v16
	s_nop 4
	s_sub_u32 s0, s0, 0x90000
	s_subb_u32 s1, s1, 0
	s_mov_b32 s6, 0x12000
	s_mov_b32 s12, 0
	s_mov_b32 s11, 31
	global_load_dword v20, v12, s[0:1]
	s_add_u32 s0, s0, s6
	s_addc_u32 s1, s1, 0
	global_load_dword v21, v12, s[0:1]
	s_add_u32 s0, s0, s6
	s_addc_u32 s1, s1, 0
	global_load_dword v22, v12, s[0:1]
	s_add_u32 s0, s0, s6
	s_addc_u32 s1, s1, 0
	global_load_dword v23, v12, s[0:1]
	s_add_u32 s0, s0, s6
	s_addc_u32 s1, s1, 0
	global_load_dword v24, v12, s[0:1]
	s_add_u32 s0, s0, s6
	s_addc_u32 s1, s1, 0
	global_load_dword v25, v12, s[0:1]
	s_add_u32 s0, s0, s6
	s_addc_u32 s1, s1, 0
	global_load_dword v26, v12, s[0:1]
	s_add_u32 s0, s0, s6
	s_addc_u32 s1, s1, 0
	global_load_dword v27, v12, s[0:1]
	s_add_u32 s0, s0, s6
	s_addc_u32 s1, s1, 0
	global_load_dword v28, v12, s[0:1]
	s_add_u32 s0, s0, s6
	s_addc_u32 s1, s1, 0
	global_load_dword v29, v12, s[0:1]
	s_add_u32 s0, s0, s6
	s_addc_u32 s1, s1, 0
	global_load_dword v30, v12, s[0:1]
	s_add_u32 s0, s0, s6
	s_addc_u32 s1, s1, 0
	global_load_dword v31, v12, s[0:1]
	s_add_u32 s0, s0, s6
	s_addc_u32 s1, s1, 0
	global_load_dword v32, v12, s[0:1]
	s_add_u32 s0, s0, s6
	s_addc_u32 s1, s1, 0
	global_load_dword v33, v12, s[0:1]
	s_add_u32 s0, s0, s6
	s_addc_u32 s1, s1, 0
	global_load_dword v34, v12, s[0:1]
	s_add_u32 s0, s0, s6
	s_addc_u32 s1, s1, 0
	global_load_dword v35, v12, s[0:1]
	s_add_u32 s0, s0, s6
	s_addc_u32 s1, s1, 0
	global_load_dword v36, v12, s[0:1]
	s_add_u32 s0, s0, s6
	s_addc_u32 s1, s1, 0
	global_load_dword v37, v12, s[0:1]
	s_add_u32 s0, s0, s6
	s_addc_u32 s1, s1, 0
	global_load_dword v38, v12, s[0:1]
	s_add_u32 s0, s0, s6
	s_addc_u32 s1, s1, 0
	global_load_dword v39, v12, s[0:1]
	s_add_u32 s0, s0, s6
	s_addc_u32 s1, s1, 0
	global_load_dword v40, v12, s[0:1]
	s_add_u32 s0, s0, s6
	s_addc_u32 s1, s1, 0
	global_load_dword v41, v12, s[0:1]
	s_add_u32 s0, s0, s6
	s_addc_u32 s1, s1, 0
	global_load_dword v42, v12, s[0:1]
	s_add_u32 s0, s0, s6
	s_addc_u32 s1, s1, 0
	global_load_dword v43, v12, s[0:1]
	s_add_u32 s0, s0, s6
	s_addc_u32 s1, s1, 0
	global_load_dword v44, v12, s[0:1]
	s_add_u32 s0, s0, s6
	s_addc_u32 s1, s1, 0
	global_load_dword v45, v12, s[0:1]
	s_add_u32 s0, s0, s6
	s_addc_u32 s1, s1, 0
	global_load_dword v46, v12, s[0:1]
	s_add_u32 s0, s0, s6
	s_addc_u32 s1, s1, 0
	global_load_dword v47, v12, s[0:1]
	s_add_u32 s0, s0, s6
	s_addc_u32 s1, s1, 0
	global_load_dword v48, v12, s[0:1]
	s_add_u32 s0, s0, s6
	s_addc_u32 s1, s1, 0
	global_load_dword v49, v12, s[0:1]
	s_add_u32 s0, s0, s6
	s_addc_u32 s1, s1, 0
	global_load_dword v50, v12, s[0:1]
	s_add_u32 s0, s0, s6
	s_addc_u32 s1, s1, 0
	global_load_dword v51, v12, s[0:1]
	s_add_u32 s0, s0, s6
	s_addc_u32 s1, s1, 0
	global_load_dword v52, v12, s[0:1]
	s_add_u32 s0, s0, s6
	s_addc_u32 s1, s1, 0
	global_load_dword v53, v12, s[0:1]
	s_add_u32 s0, s0, s6
	s_addc_u32 s1, s1, 0
	global_load_dword v54, v12, s[0:1]
	s_add_u32 s0, s0, s6
	s_addc_u32 s1, s1, 0
	global_load_dword v55, v12, s[0:1]
	s_add_u32 s0, s0, s6
	s_addc_u32 s1, s1, 0
	global_load_dword v56, v12, s[0:1]
	s_add_u32 s0, s0, s6
	s_addc_u32 s1, s1, 0
	global_load_dword v57, v12, s[0:1]
	s_add_u32 s0, s0, s6
	s_addc_u32 s1, s1, 0
	global_load_dword v58, v12, s[0:1]
	s_add_u32 s0, s0, s6
	s_addc_u32 s1, s1, 0
	global_load_dword v59, v12, s[0:1]
	s_add_u32 s0, s0, s6
	s_addc_u32 s1, s1, 0
	global_load_dword v60, v12, s[0:1]
	s_add_u32 s0, s0, s6
	s_addc_u32 s1, s1, 0
	global_load_dword v61, v12, s[0:1]
	s_add_u32 s0, s0, s6
	s_addc_u32 s1, s1, 0
	global_load_dword v62, v12, s[0:1]
	s_add_u32 s0, s0, s6
	s_addc_u32 s1, s1, 0
	global_load_dword v63, v12, s[0:1]
	s_add_u32 s0, s0, s6
	s_addc_u32 s1, s1, 0
	global_load_dword v64, v12, s[0:1]
	s_add_u32 s0, s0, s6
	s_addc_u32 s1, s1, 0
	global_load_dword v65, v12, s[0:1]
	s_add_u32 s0, s0, s6
	s_addc_u32 s1, s1, 0
	global_load_dword v66, v12, s[0:1]
	s_add_u32 s0, s0, s6
	s_addc_u32 s1, s1, 0
	global_load_dword v67, v12, s[0:1]
	s_add_u32 s0, s0, s6
	s_addc_u32 s1, s1, 0
; #define LAS __attribute__((address_space(3)))
; __device__ __forceinline__ void phase_prologue(const In& in, unsigned char* ws, LAS unsigned char* lds, int tid, int wave, int lane) {
;     ...
;             for (int k0 = 0; k0 < D; k0 += 16) {
;                 float w[16];
; #pragma unroll
;                 for (int j = 0; j < 16; ++j) w[j] = W[(size_t)(k0 + j) * NMOD];
; #pragma unroll
;                 for (int j = 0; j < 16; ++j) { const f32x4 c0 = *(const LAS f32x4*)(condT + (k0 + j) * 8), c1 = *(const LAS f32x4*)(condT + (k0 + j) * 8 + 4);
;                     acc[0] += c0[0] * w[j]; acc[1] += c0[1] * w[j]; acc[2] += c0[2] * w[j]; acc[3] += c0[3] * w[j];
;                     acc[4] += c1[0] * w[j]; acc[5] += c1[1] * w[j]; acc[6] += c1[2] * w[j]; acc[7] += c1[3] * w[j]; }
.Lada_loop:
	s_waitcnt vmcnt(32)
	global_load_dword v68, v12, s[0:1]
	s_add_u32 s0, s0, s6
	s_addc_u32 s1, s1, 0
	global_load_dword v69, v12, s[0:1]
	s_add_u32 s0, s0, s6
	s_addc_u32 s1, s1, 0
	global_load_dword v70, v12, s[0:1]
	s_add_u32 s0, s0, s6
	s_addc_u32 s1, s1, 0
	global_load_dword v71, v12, s[0:1]
	s_add_u32 s0, s0, s6
	s_addc_u32 s1, s1, 0
	global_load_dword v72, v12, s[0:1]
	s_add_u32 s0, s0, s6
	s_addc_u32 s1, s1, 0
	global_load_dword v73, v12, s[0:1]
	s_add_u32 s0, s0, s6
	s_addc_u32 s1, s1, 0
	global_load_dword v74, v12, s[0:1]
	s_add_u32 s0, s0, s6
	s_addc_u32 s1, s1, 0
	global_load_dword v75, v12, s[0:1]
	s_add_u32 s0, s0, s6
	s_addc_u32 s1, s1, 0
	global_load_dword v76, v12, s[0:1]
	s_add_u32 s0, s0, s6
	s_addc_u32 s1, s1, 0
	global_load_dword v77, v12, s[0:1]
	s_add_u32 s0, s0, s6
	s_addc_u32 s1, s1, 0
	global_load_dword v78, v12, s[0:1]
	s_add_u32 s0, s0, s6
	s_addc_u32 s1, s1, 0
	global_load_dword v79, v12, s[0:1]
	s_add_u32 s0, s0, s6
	s_addc_u32 s1, s1, 0
	global_load_dword v80, v12, s[0:1]
	s_add_u32 s0, s0, s6
	s_addc_u32 s1, s1, 0
	global_load_dword v81, v12, s[0:1]
	s_add_u32 s0, s0, s6
	s_addc_u32 s1, s1, 0
	global_load_dword v82, v12, s[0:1]
	s_add_u32 s0, s0, s6
	s_addc_u32 s1, s1, 0
	global_load_dword v83, v12, s[0:1]
	s_add_u32 s0, s0, s6
	s_addc_u32 s1, s1, 0
	v_mov_b32_e32 v13, s12
	s_addk_i32 s12, 0x200
	ds_read_b128 v[84:87], v13
	ds_read_b128 v[88:91], v13 offset:16
	ds_read_b128 v[92:95], v13 offset:32
	ds_read_b128 v[96:99], v13 offset:48
	ds_read_b128 v[100:103], v13 offset:64
	ds_read_b128 v[104:107], v13 offset:80
	ds_read_b128 v[108:111], v13 offset:96
	ds_read_b128 v[112:115], v13 offset:112
	ds_read_b128 v[116:119], v13 offset:128
	ds_read_b128 v[120:123], v13 offset:144
	ds_read_b128 v[124:127], v13 offset:160
	ds_read_b128 v[128:131], v13 offset:176
	ds_read_b128 v[132:135], v13 offset:192
	ds_read_b128 v[136:139], v13 offset:208
	ds_read_b128 v[140:143], v13 offset:224
	ds_read_b128 v[144:147], v13 offset:240
	ds_read_b128 v[148:151], v13 offset:256
	ds_read_b128 v[152:155], v13 offset:272
	ds_read_b128 v[156:159], v13 offset:288
	ds_read_b128 v[160:163], v13 offset:304
	ds_read_b128 v[164:167], v13 offset:320
	ds_read_b128 v[168:171], v13 offset:336
	ds_read_b128 v[172:175], v13 offset:352
	ds_read_b128 v[176:179], v13 offset:368
	ds_read_b128 v[180:183], v13 offset:384
	ds_read_b128 v[184:187], v13 offset:400
	ds_read_b128 v[188:191], v13 offset:416
	ds_read_b128 v[192:195], v13 offset:432
	ds_read_b128 v[196:199], v13 offset:448
	ds_read_b128 v[200:203], v13 offset:464
	ds_read_b128 v[204:207], v13 offset:480
	ds_read_b128 v[208:211], v13 offset:496
	s_waitcnt lgkmcnt(15)
	v_fmac_f32_e32 v10, v20, v84
	v_fmac_f32_e32 v11, v20, v85
	v_fmac_f32_e32 v8, v20, v86
	v_fmac_f32_e32 v9, v20, v87
	v_fmac_f32_e32 v6, v20, v88
	v_fmac_f32_e32 v7, v20, v89
	v_fmac_f32_e32 v4, v20, v90
	v_fmac_f32_e32 v5, v20, v91
	s_waitcnt lgkmcnt(15)
	v_fmac_f32_e32 v10, v21, v92
	v_fmac_f32_e32 v11, v21, v93
	v_fmac_f32_e32 v8, v21, v94
	v_fmac_f32_e32 v9, v21, v95
	v_fmac_f32_e32 v6, v21, v96
	v_fmac_f32_e32 v7, v21, v97
	v_fmac_f32_e32 v4, v21, v98
	v_fmac_f32_e32 v5, v21, v99
	s_waitcnt lgkmcnt(15)
	v_fmac_f32_e32 v10, v22, v100
	v_fmac_f32_e32 v11, v22, v101
	v_fmac_f32_e32 v8, v22, v102
	v_fmac_f32_e32 v9, v22, v103
	v_fmac_f32_e32 v6, v22, v104
	v_fmac_f32_e32 v7, v22, v105
	v_fmac_f32_e32 v4, v22, v106
	v_fmac_f32_e32 v5, v22, v107
	s_waitcnt lgkmcnt(15)
	v_fmac_f32_e32 v10, v23, v108
	v_fmac_f32_e32 v11, v23, v109
	v_fmac_f32_e32 v8, v23, v110
	v_fmac_f32_e32 v9, v23, v111
	v_fmac_f32_e32 v6, v23, v112
	v_fmac_f32_e32 v7, v23, v113
	v_fmac_f32_e32 v4, v23, v114
	v_fmac_f32_e32 v5, v23, v115
	s_waitcnt lgkmcnt(15)
	v_fmac_f32_e32 v10, v24, v116
	v_fmac_f32_e32 v11, v24, v117
	v_fmac_f32_e32 v8, v24, v118
	v_fmac_f32_e32 v9, v24, v119
	v_fmac_f32_e32 v6, v24, v120
	v_fmac_f32_e32 v7, v24, v121
	v_fmac_f32_e32 v4, v24, v122
	v_fmac_f32_e32 v5, v24, v123
	s_waitcnt lgkmcnt(15)
	v_fmac_f32_e32 v10, v25, v124
	v_fmac_f32_e32 v11, v25, v125
	v_fmac_f32_e32 v8, v25, v126
	v_fmac_f32_e32 v9, v25, v127
	v_fmac_f32_e32 v6, v25, v128
	v_fmac_f32_e32 v7, v25, v129
	v_fmac_f32_e32 v4, v25, v130
	v_fmac_f32_e32 v5, v25, v131
	s_waitcnt lgkmcnt(15)
	v_fmac_f32_e32 v10, v26, v132
	v_fmac_f32_e32 v11, v26, v133
	v_fmac_f32_e32 v8, v26, v134
	v_fmac_f32_e32 v9, v26, v135
	v_fmac_f32_e32 v6, v26, v136
	v_fmac_f32_e32 v7, v26, v137
	v_fmac_f32_e32 v4, v26, v138
	v_fmac_f32_e32 v5, v26, v139
	s_waitcnt lgkmcnt(15)
	v_fmac_f32_e32 v10, v27, v140
	v_fmac_f32_e32 v11, v27, v141
	v_fmac_f32_e32 v8, v27, v142
	v_fmac_f32_e32 v9, v27, v143
	v_fmac_f32_e32 v6, v27, v144
	v_fmac_f32_e32 v7, v27, v145
	v_fmac_f32_e32 v4, v27, v146
	v_fmac_f32_e32 v5, v27, v147
	s_waitcnt lgkmcnt(14)
	v_fmac_f32_e32 v10, v28, v148
	v_fmac_f32_e32 v11, v28, v149
	v_fmac_f32_e32 v8, v28, v150
	v_fmac_f32_e32 v9, v28, v151
	v_fmac_f32_e32 v6, v28, v152
	v_fmac_f32_e32 v7, v28, v153
	v_fmac_f32_e32 v4, v28, v154
	v_fmac_f32_e32 v5, v28, v155
	s_waitcnt lgkmcnt(12)
	v_fmac_f32_e32 v10, v29, v156
	v_fmac_f32_e32 v11, v29, v157
	v_fmac_f32_e32 v8, v29, v158
	v_fmac_f32_e32 v9, v29, v159
	v_fmac_f32_e32 v6, v29, v160
	v_fmac_f32_e32 v7, v29, v161
	v_fmac_f32_e32 v4, v29, v162
	v_fmac_f32_e32 v5, v29, v163
	s_waitcnt lgkmcnt(10)
	v_fmac_f32_e32 v10, v30, v164
	v_fmac_f32_e32 v11, v30, v165
	v_fmac_f32_e32 v8, v30, v166
	v_fmac_f32_e32 v9, v30, v167
	v_fmac_f32_e32 v6, v30, v168
	v_fmac_f32_e32 v7, v30, v169
	v_fmac_f32_e32 v4, v30, v170
	v_fmac_f32_e32 v5, v30, v171
	s_waitcnt lgkmcnt(8)
; #define LAS __attribute__((address_space(3)))
; __device__ __forceinline__ void phase_prologue(const In& in, unsigned char* ws, LAS unsigned char* lds, int tid, int wave, int lane) {
;     ...
;             for (int k0 = 0; k0 < D; k0 += 16) {
;                 float w[16];
; #pragma unroll
;                 for (int j = 0; j < 16; ++j) w[j] = W[(size_t)(k0 + j) * NMOD];
; #pragma unroll
;                 for (int j = 0; j < 16; ++j) { const f32x4 c0 = *(const LAS f32x4*)(condT + (k0 + j) * 8), c1 = *(const LAS f32x4*)(condT + (k0 + j) * 8 + 4);
;                     acc[0] += c0[0] * w[j]; acc[1] += c0[1] * w[j]; acc[2] += c0[2] * w[j]; acc[3] += c0[3] * w[j];
;                     acc[4] += c1[0] * w[j]; acc[5] += c1[1] * w[j]; acc[6] += c1[2] * w[j]; acc[7] += c1[3] * w[j]; }
	v_fmac_f32_e32 v10, v31, v172
	v_fmac_f32_e32 v11, v31, v173
	v_fmac_f32_e32 v8, v31, v174
	v_fmac_f32_e32 v9, v31, v175
	v_fmac_f32_e32 v6, v31, v176
	v_fmac_f32_e32 v7, v31, v177
	v_fmac_f32_e32 v4, v31, v178
	v_fmac_f32_e32 v5, v31, v179
	s_waitcnt lgkmcnt(6)
	v_fmac_f32_e32 v10, v32, v180
	v_fmac_f32_e32 v11, v32, v181
	v_fmac_f32_e32 v8, v32, v182
	v_fmac_f32_e32 v9, v32, v183
	v_fmac_f32_e32 v6, v32, v184
	v_fmac_f32_e32 v7, v32, v185
	v_fmac_f32_e32 v4, v32, v186
	v_fmac_f32_e32 v5, v32, v187
	s_waitcnt lgkmcnt(4)
	v_fmac_f32_e32 v10, v33, v188
	v_fmac_f32_e32 v11, v33, v189
	v_fmac_f32_e32 v8, v33, v190
	v_fmac_f32_e32 v9, v33, v191
	v_fmac_f32_e32 v6, v33, v192
	v_fmac_f32_e32 v7, v33, v193
	v_fmac_f32_e32 v4, v33, v194
	v_fmac_f32_e32 v5, v33, v195
	s_waitcnt lgkmcnt(2)
	v_fmac_f32_e32 v10, v34, v196
	v_fmac_f32_e32 v11, v34, v197
	v_fmac_f32_e32 v8, v34, v198
	v_fmac_f32_e32 v9, v34, v199
	v_fmac_f32_e32 v6, v34, v200
	v_fmac_f32_e32 v7, v34, v201
	v_fmac_f32_e32 v4, v34, v202
	v_fmac_f32_e32 v5, v34, v203
	s_waitcnt lgkmcnt(0)
	v_fmac_f32_e32 v10, v35, v204
	v_fmac_f32_e32 v11, v35, v205
	v_fmac_f32_e32 v8, v35, v206
	v_fmac_f32_e32 v9, v35, v207
	v_fmac_f32_e32 v6, v35, v208
	v_fmac_f32_e32 v7, v35, v209
	v_fmac_f32_e32 v4, v35, v210
	v_fmac_f32_e32 v5, v35, v211
	s_waitcnt vmcnt(32)
	global_load_dword v20, v12, s[0:1]
	s_add_u32 s0, s0, s6
	s_addc_u32 s1, s1, 0
	global_load_dword v21, v12, s[0:1]
	s_add_u32 s0, s0, s6
	s_addc_u32 s1, s1, 0
	global_load_dword v22, v12, s[0:1]
	s_add_u32 s0, s0, s6
	s_addc_u32 s1, s1, 0
	global_load_dword v23, v12, s[0:1]
	s_add_u32 s0, s0, s6
	s_addc_u32 s1, s1, 0
	global_load_dword v24, v12, s[0:1]
	s_add_u32 s0, s0, s6
	s_addc_u32 s1, s1, 0
	global_load_dword v25, v12, s[0:1]
	s_add_u32 s0, s0, s6
	s_addc_u32 s1, s1, 0
	global_load_dword v26, v12, s[0:1]
	s_add_u32 s0, s0, s6
	s_addc_u32 s1, s1, 0
	global_load_dword v27, v12, s[0:1]
	s_add_u32 s0, s0, s6
	s_addc_u32 s1, s1, 0
	global_load_dword v28, v12, s[0:1]
	s_add_u32 s0, s0, s6
	s_addc_u32 s1, s1, 0
	global_load_dword v29, v12, s[0:1]
	s_add_u32 s0, s0, s6
	s_addc_u32 s1, s1, 0
	global_load_dword v30, v12, s[0:1]
	s_add_u32 s0, s0, s6
	s_addc_u32 s1, s1, 0
	global_load_dword v31, v12, s[0:1]
	s_add_u32 s0, s0, s6
	s_addc_u32 s1, s1, 0
	global_load_dword v32, v12, s[0:1]
	s_add_u32 s0, s0, s6
	s_addc_u32 s1, s1, 0
	global_load_dword v33, v12, s[0:1]
	s_add_u32 s0, s0, s6
	s_addc_u32 s1, s1, 0
	global_load_dword v34, v12, s[0:1]
	s_add_u32 s0, s0, s6
	s_addc_u32 s1, s1, 0
	global_load_dword v35, v12, s[0:1]
	s_add_u32 s0, s0, s6
	s_addc_u32 s1, s1, 0
	v_mov_b32_e32 v13, s12
	s_addk_i32 s12, 0x200
	ds_read_b128 v[84:87], v13
	ds_read_b128 v[88:91], v13 offset:16
	ds_read_b128 v[92:95], v13 offset:32
	ds_read_b128 v[96:99], v13 offset:48
	ds_read_b128 v[100:103], v13 offset:64
	ds_read_b128 v[104:107], v13 offset:80
	ds_read_b128 v[108:111], v13 offset:96
	ds_read_b128 v[112:115], v13 offset:112
	ds_read_b128 v[116:119], v13 offset:128
	ds_read_b128 v[120:123], v13 offset:144
	ds_read_b128 v[124:127], v13 offset:160
	ds_read_b128 v[128:131], v13 offset:176
	ds_read_b128 v[132:135], v13 offset:192
	ds_read_b128 v[136:139], v13 offset:208
	ds_read_b128 v[140:143], v13 offset:224
	ds_read_b128 v[144:147], v13 offset:240
	ds_read_b128 v[148:151], v13 offset:256
	ds_read_b128 v[152:155], v13 offset:272
	ds_read_b128 v[156:159], v13 offset:288
	ds_read_b128 v[160:163], v13 offset:304
	ds_read_b128 v[164:167], v13 offset:320
	ds_read_b128 v[168:171], v13 offset:336
	ds_read_b128 v[172:175], v13 offset:352
	ds_read_b128 v[176:179], v13 offset:368
	ds_read_b128 v[180:183], v13 offset:384
	ds_read_b128 v[184:187], v13 offset:400
	ds_read_b128 v[188:191], v13 offset:416
	ds_read_b128 v[192:195], v13 offset:432
	ds_read_b128 v[196:199], v13 offset:448
	ds_read_b128 v[200:203], v13 offset:464
	ds_read_b128 v[204:207], v13 offset:480
	ds_read_b128 v[208:211], v13 offset:496
	s_waitcnt lgkmcnt(15)
	v_fmac_f32_e32 v10, v36, v84
	v_fmac_f32_e32 v11, v36, v85
	v_fmac_f32_e32 v8, v36, v86
	v_fmac_f32_e32 v9, v36, v87
	v_fmac_f32_e32 v6, v36, v88
	v_fmac_f32_e32 v7, v36, v89
	v_fmac_f32_e32 v4, v36, v90
	v_fmac_f32_e32 v5, v36, v91
	s_waitcnt lgkmcnt(15)
	v_fmac_f32_e32 v10, v37, v92
	v_fmac_f32_e32 v11, v37, v93
	v_fmac_f32_e32 v8, v37, v94
	v_fmac_f32_e32 v9, v37, v95
	v_fmac_f32_e32 v6, v37, v96
	v_fmac_f32_e32 v7, v37, v97
	v_fmac_f32_e32 v4, v37, v98
	v_fmac_f32_e32 v5, v37, v99
	s_waitcnt lgkmcnt(15)
	v_fmac_f32_e32 v10, v38, v100
	v_fmac_f32_e32 v11, v38, v101
	v_fmac_f32_e32 v8, v38, v102
	v_fmac_f32_e32 v9, v38, v103
	v_fmac_f32_e32 v6, v38, v104
	v_fmac_f32_e32 v7, v38, v105
	v_fmac_f32_e32 v4, v38, v106
	v_fmac_f32_e32 v5, v38, v107
	s_waitcnt lgkmcnt(15)
	v_fmac_f32_e32 v10, v39, v108
	v_fmac_f32_e32 v11, v39, v109
	v_fmac_f32_e32 v8, v39, v110
	v_fmac_f32_e32 v9, v39, v111
	v_fmac_f32_e32 v6, v39, v112
	v_fmac_f32_e32 v7, v39, v113
	v_fmac_f32_e32 v4, v39, v114
	v_fmac_f32_e32 v5, v39, v115
	s_waitcnt lgkmcnt(15)
	v_fmac_f32_e32 v10, v40, v116
	v_fmac_f32_e32 v11, v40, v117
	v_fmac_f32_e32 v8, v40, v118
	v_fmac_f32_e32 v9, v40, v119
	v_fmac_f32_e32 v6, v40, v120
	v_fmac_f32_e32 v7, v40, v121
	v_fmac_f32_e32 v4, v40, v122
	v_fmac_f32_e32 v5, v40, v123
	s_waitcnt lgkmcnt(15)
	v_fmac_f32_e32 v10, v41, v124
	v_fmac_f32_e32 v11, v41, v125
	v_fmac_f32_e32 v8, v41, v126
	v_fmac_f32_e32 v9, v41, v127
	v_fmac_f32_e32 v6, v41, v128
	v_fmac_f32_e32 v7, v41, v129
	v_fmac_f32_e32 v4, v41, v130
	v_fmac_f32_e32 v5, v41, v131
	s_waitcnt lgkmcnt(15)
; #define LAS __attribute__((address_space(3)))
; __device__ __forceinline__ void phase_prologue(const In& in, unsigned char* ws, LAS unsigned char* lds, int tid, int wave, int lane) {
;     ...
;             for (int k0 = 0; k0 < D; k0 += 16) {
;                 float w[16];
; #pragma unroll
;                 for (int j = 0; j < 16; ++j) w[j] = W[(size_t)(k0 + j) * NMOD];
; #pragma unroll
;                 for (int j = 0; j < 16; ++j) { const f32x4 c0 = *(const LAS f32x4*)(condT + (k0 + j) * 8), c1 = *(const LAS f32x4*)(condT + (k0 + j) * 8 + 4);
;                     acc[0] += c0[0] * w[j]; acc[1] += c0[1] * w[j]; acc[2] += c0[2] * w[j]; acc[3] += c0[3] * w[j];
;                     acc[4] += c1[0] * w[j]; acc[5] += c1[1] * w[j]; acc[6] += c1[2] * w[j]; acc[7] += c1[3] * w[j]; }
	v_fmac_f32_e32 v10, v42, v132
	v_fmac_f32_e32 v11, v42, v133
	v_fmac_f32_e32 v8, v42, v134
	v_fmac_f32_e32 v9, v42, v135
	v_fmac_f32_e32 v6, v42, v136
	v_fmac_f32_e32 v7, v42, v137
	v_fmac_f32_e32 v4, v42, v138
	v_fmac_f32_e32 v5, v42, v139
	s_waitcnt lgkmcnt(15)
	v_fmac_f32_e32 v10, v43, v140
	v_fmac_f32_e32 v11, v43, v141
	v_fmac_f32_e32 v8, v43, v142
	v_fmac_f32_e32 v9, v43, v143
	v_fmac_f32_e32 v6, v43, v144
	v_fmac_f32_e32 v7, v43, v145
	v_fmac_f32_e32 v4, v43, v146
	v_fmac_f32_e32 v5, v43, v147
	s_waitcnt lgkmcnt(14)
	v_fmac_f32_e32 v10, v44, v148
	v_fmac_f32_e32 v11, v44, v149
	v_fmac_f32_e32 v8, v44, v150
	v_fmac_f32_e32 v9, v44, v151
	v_fmac_f32_e32 v6, v44, v152
	v_fmac_f32_e32 v7, v44, v153
	v_fmac_f32_e32 v4, v44, v154
	v_fmac_f32_e32 v5, v44, v155
	s_waitcnt lgkmcnt(12)
	v_fmac_f32_e32 v10, v45, v156
	v_fmac_f32_e32 v11, v45, v157
	v_fmac_f32_e32 v8, v45, v158
	v_fmac_f32_e32 v9, v45, v159
	v_fmac_f32_e32 v6, v45, v160
	v_fmac_f32_e32 v7, v45, v161
	v_fmac_f32_e32 v4, v45, v162
	v_fmac_f32_e32 v5, v45, v163
	s_waitcnt lgkmcnt(10)
	v_fmac_f32_e32 v10, v46, v164
	v_fmac_f32_e32 v11, v46, v165
	v_fmac_f32_e32 v8, v46, v166
	v_fmac_f32_e32 v9, v46, v167
	v_fmac_f32_e32 v6, v46, v168
	v_fmac_f32_e32 v7, v46, v169
	v_fmac_f32_e32 v4, v46, v170
	v_fmac_f32_e32 v5, v46, v171
	s_waitcnt lgkmcnt(8)
	v_fmac_f32_e32 v10, v47, v172
	v_fmac_f32_e32 v11, v47, v173
	v_fmac_f32_e32 v8, v47, v174
	v_fmac_f32_e32 v9, v47, v175
	v_fmac_f32_e32 v6, v47, v176
	v_fmac_f32_e32 v7, v47, v177
	v_fmac_f32_e32 v4, v47, v178
	v_fmac_f32_e32 v5, v47, v179
	s_waitcnt lgkmcnt(6)
	v_fmac_f32_e32 v10, v48, v180
	v_fmac_f32_e32 v11, v48, v181
	v_fmac_f32_e32 v8, v48, v182
	v_fmac_f32_e32 v9, v48, v183
	v_fmac_f32_e32 v6, v48, v184
	v_fmac_f32_e32 v7, v48, v185
	v_fmac_f32_e32 v4, v48, v186
	v_fmac_f32_e32 v5, v48, v187
	s_waitcnt lgkmcnt(4)
	v_fmac_f32_e32 v10, v49, v188
	v_fmac_f32_e32 v11, v49, v189
	v_fmac_f32_e32 v8, v49, v190
	v_fmac_f32_e32 v9, v49, v191
	v_fmac_f32_e32 v6, v49, v192
	v_fmac_f32_e32 v7, v49, v193
	v_fmac_f32_e32 v4, v49, v194
	v_fmac_f32_e32 v5, v49, v195
	s_waitcnt lgkmcnt(2)
	v_fmac_f32_e32 v10, v50, v196
	v_fmac_f32_e32 v11, v50, v197
	v_fmac_f32_e32 v8, v50, v198
	v_fmac_f32_e32 v9, v50, v199
	v_fmac_f32_e32 v6, v50, v200
	v_fmac_f32_e32 v7, v50, v201
	v_fmac_f32_e32 v4, v50, v202
	v_fmac_f32_e32 v5, v50, v203
	s_waitcnt lgkmcnt(0)
	v_fmac_f32_e32 v10, v51, v204
	v_fmac_f32_e32 v11, v51, v205
	v_fmac_f32_e32 v8, v51, v206
	v_fmac_f32_e32 v9, v51, v207
	v_fmac_f32_e32 v6, v51, v208
	v_fmac_f32_e32 v7, v51, v209
	v_fmac_f32_e32 v4, v51, v210
	v_fmac_f32_e32 v5, v51, v211
	s_waitcnt vmcnt(32)
	global_load_dword v36, v12, s[0:1]
	s_add_u32 s0, s0, s6
	s_addc_u32 s1, s1, 0
	global_load_dword v37, v12, s[0:1]
	s_add_u32 s0, s0, s6
	s_addc_u32 s1, s1, 0
	global_load_dword v38, v12, s[0:1]
	s_add_u32 s0, s0, s6
	s_addc_u32 s1, s1, 0
	global_load_dword v39, v12, s[0:1]
	s_add_u32 s0, s0, s6
	s_addc_u32 s1, s1, 0
	global_load_dword v40, v12, s[0:1]
	s_add_u32 s0, s0, s6
	s_addc_u32 s1, s1, 0
	global_load_dword v41, v12, s[0:1]
	s_add_u32 s0, s0, s6
	s_addc_u32 s1, s1, 0
	global_load_dword v42, v12, s[0:1]
	s_add_u32 s0, s0, s6
	s_addc_u32 s1, s1, 0
	global_load_dword v43, v12, s[0:1]
	s_add_u32 s0, s0, s6
	s_addc_u32 s1, s1, 0
	global_load_dword v44, v12, s[0:1]
	s_add_u32 s0, s0, s6
	s_addc_u32 s1, s1, 0
	global_load_dword v45, v12, s[0:1]
	s_add_u32 s0, s0, s6
	s_addc_u32 s1, s1, 0
	global_load_dword v46, v12, s[0:1]
	s_add_u32 s0, s0, s6
	s_addc_u32 s1, s1, 0
	global_load_dword v47, v12, s[0:1]
	s_add_u32 s0, s0, s6
	s_addc_u32 s1, s1, 0
	global_load_dword v48, v12, s[0:1]
	s_add_u32 s0, s0, s6
	s_addc_u32 s1, s1, 0
	global_load_dword v49, v12, s[0:1]
	s_add_u32 s0, s0, s6
	s_addc_u32 s1, s1, 0
	global_load_dword v50, v12, s[0:1]
	s_add_u32 s0, s0, s6
	s_addc_u32 s1, s1, 0
	global_load_dword v51, v12, s[0:1]
	s_add_u32 s0, s0, s6
	s_addc_u32 s1, s1, 0
	v_mov_b32_e32 v13, s12
	s_addk_i32 s12, 0x200
	ds_read_b128 v[84:87], v13
	ds_read_b128 v[88:91], v13 offset:16
	ds_read_b128 v[92:95], v13 offset:32
	ds_read_b128 v[96:99], v13 offset:48
	ds_read_b128 v[100:103], v13 offset:64
	ds_read_b128 v[104:107], v13 offset:80
	ds_read_b128 v[108:111], v13 offset:96
	ds_read_b128 v[112:115], v13 offset:112
	ds_read_b128 v[116:119], v13 offset:128
	ds_read_b128 v[120:123], v13 offset:144
	ds_read_b128 v[124:127], v13 offset:160
	ds_read_b128 v[128:131], v13 offset:176
	ds_read_b128 v[132:135], v13 offset:192
	ds_read_b128 v[136:139], v13 offset:208
	ds_read_b128 v[140:143], v13 offset:224
	ds_read_b128 v[144:147], v13 offset:240
	ds_read_b128 v[148:151], v13 offset:256
	ds_read_b128 v[152:155], v13 offset:272
	ds_read_b128 v[156:159], v13 offset:288
	ds_read_b128 v[160:163], v13 offset:304
	ds_read_b128 v[164:167], v13 offset:320
	ds_read_b128 v[168:171], v13 offset:336
	ds_read_b128 v[172:175], v13 offset:352
	ds_read_b128 v[176:179], v13 offset:368
	ds_read_b128 v[180:183], v13 offset:384
	ds_read_b128 v[184:187], v13 offset:400
	ds_read_b128 v[188:191], v13 offset:416
	ds_read_b128 v[192:195], v13 offset:432
	ds_read_b128 v[196:199], v13 offset:448
	ds_read_b128 v[200:203], v13 offset:464
	ds_read_b128 v[204:207], v13 offset:480
	ds_read_b128 v[208:211], v13 offset:496
	s_waitcnt lgkmcnt(15)
	v_fmac_f32_e32 v10, v52, v84
	v_fmac_f32_e32 v11, v52, v85
	v_fmac_f32_e32 v8, v52, v86
	v_fmac_f32_e32 v9, v52, v87
	v_fmac_f32_e32 v6, v52, v88
	v_fmac_f32_e32 v7, v52, v89
	v_fmac_f32_e32 v4, v52, v90
	v_fmac_f32_e32 v5, v52, v91
	s_waitcnt lgkmcnt(15)
; #define LAS __attribute__((address_space(3)))
; __device__ __forceinline__ void phase_prologue(const In& in, unsigned char* ws, LAS unsigned char* lds, int tid, int wave, int lane) {
;     ...
;             for (int k0 = 0; k0 < D; k0 += 16) {
;                 float w[16];
; #pragma unroll
;                 for (int j = 0; j < 16; ++j) w[j] = W[(size_t)(k0 + j) * NMOD];
; #pragma unroll
;                 for (int j = 0; j < 16; ++j) { const f32x4 c0 = *(const LAS f32x4*)(condT + (k0 + j) * 8), c1 = *(const LAS f32x4*)(condT + (k0 + j) * 8 + 4);
;                     acc[0] += c0[0] * w[j]; acc[1] += c0[1] * w[j]; acc[2] += c0[2] * w[j]; acc[3] += c0[3] * w[j];
;                     acc[4] += c1[0] * w[j]; acc[5] += c1[1] * w[j]; acc[6] += c1[2] * w[j]; acc[7] += c1[3] * w[j]; }
	v_fmac_f32_e32 v10, v53, v92
	v_fmac_f32_e32 v11, v53, v93
	v_fmac_f32_e32 v8, v53, v94
	v_fmac_f32_e32 v9, v53, v95
	v_fmac_f32_e32 v6, v53, v96
	v_fmac_f32_e32 v7, v53, v97
	v_fmac_f32_e32 v4, v53, v98
	v_fmac_f32_e32 v5, v53, v99
	s_waitcnt lgkmcnt(15)
	v_fmac_f32_e32 v10, v54, v100
	v_fmac_f32_e32 v11, v54, v101
	v_fmac_f32_e32 v8, v54, v102
	v_fmac_f32_e32 v9, v54, v103
	v_fmac_f32_e32 v6, v54, v104
	v_fmac_f32_e32 v7, v54, v105
	v_fmac_f32_e32 v4, v54, v106
	v_fmac_f32_e32 v5, v54, v107
	s_waitcnt lgkmcnt(15)
	v_fmac_f32_e32 v10, v55, v108
	v_fmac_f32_e32 v11, v55, v109
	v_fmac_f32_e32 v8, v55, v110
	v_fmac_f32_e32 v9, v55, v111
	v_fmac_f32_e32 v6, v55, v112
	v_fmac_f32_e32 v7, v55, v113
	v_fmac_f32_e32 v4, v55, v114
	v_fmac_f32_e32 v5, v55, v115
	s_waitcnt lgkmcnt(15)
	v_fmac_f32_e32 v10, v56, v116
	v_fmac_f32_e32 v11, v56, v117
	v_fmac_f32_e32 v8, v56, v118
	v_fmac_f32_e32 v9, v56, v119
	v_fmac_f32_e32 v6, v56, v120
	v_fmac_f32_e32 v7, v56, v121
	v_fmac_f32_e32 v4, v56, v122
	v_fmac_f32_e32 v5, v56, v123
	s_waitcnt lgkmcnt(15)
	v_fmac_f32_e32 v10, v57, v124
	v_fmac_f32_e32 v11, v57, v125
	v_fmac_f32_e32 v8, v57, v126
	v_fmac_f32_e32 v9, v57, v127
	v_fmac_f32_e32 v6, v57, v128
	v_fmac_f32_e32 v7, v57, v129
	v_fmac_f32_e32 v4, v57, v130
	v_fmac_f32_e32 v5, v57, v131
	s_waitcnt lgkmcnt(15)
	v_fmac_f32_e32 v10, v58, v132
	v_fmac_f32_e32 v11, v58, v133
	v_fmac_f32_e32 v8, v58, v134
	v_fmac_f32_e32 v9, v58, v135
	v_fmac_f32_e32 v6, v58, v136
	v_fmac_f32_e32 v7, v58, v137
	v_fmac_f32_e32 v4, v58, v138
	v_fmac_f32_e32 v5, v58, v139
	s_waitcnt lgkmcnt(15)
	v_fmac_f32_e32 v10, v59, v140
	v_fmac_f32_e32 v11, v59, v141
	v_fmac_f32_e32 v8, v59, v142
	v_fmac_f32_e32 v9, v59, v143
	v_fmac_f32_e32 v6, v59, v144
	v_fmac_f32_e32 v7, v59, v145
	v_fmac_f32_e32 v4, v59, v146
	v_fmac_f32_e32 v5, v59, v147
	s_waitcnt lgkmcnt(14)
	v_fmac_f32_e32 v10, v60, v148
	v_fmac_f32_e32 v11, v60, v149
	v_fmac_f32_e32 v8, v60, v150
	v_fmac_f32_e32 v9, v60, v151
	v_fmac_f32_e32 v6, v60, v152
	v_fmac_f32_e32 v7, v60, v153
	v_fmac_f32_e32 v4, v60, v154
	v_fmac_f32_e32 v5, v60, v155
	s_waitcnt lgkmcnt(12)
	v_fmac_f32_e32 v10, v61, v156
	v_fmac_f32_e32 v11, v61, v157
	v_fmac_f32_e32 v8, v61, v158
	v_fmac_f32_e32 v9, v61, v159
	v_fmac_f32_e32 v6, v61, v160
	v_fmac_f32_e32 v7, v61, v161
	v_fmac_f32_e32 v4, v61, v162
	v_fmac_f32_e32 v5, v61, v163
	s_waitcnt lgkmcnt(10)
	v_fmac_f32_e32 v10, v62, v164
	v_fmac_f32_e32 v11, v62, v165
	v_fmac_f32_e32 v8, v62, v166
	v_fmac_f32_e32 v9, v62, v167
	v_fmac_f32_e32 v6, v62, v168
	v_fmac_f32_e32 v7, v62, v169
	v_fmac_f32_e32 v4, v62, v170
	v_fmac_f32_e32 v5, v62, v171
	s_waitcnt lgkmcnt(8)
	v_fmac_f32_e32 v10, v63, v172
	v_fmac_f32_e32 v11, v63, v173
	v_fmac_f32_e32 v8, v63, v174
	v_fmac_f32_e32 v9, v63, v175
	v_fmac_f32_e32 v6, v63, v176
	v_fmac_f32_e32 v7, v63, v177
	v_fmac_f32_e32 v4, v63, v178
	v_fmac_f32_e32 v5, v63, v179
	s_waitcnt lgkmcnt(6)
	v_fmac_f32_e32 v10, v64, v180
	v_fmac_f32_e32 v11, v64, v181
	v_fmac_f32_e32 v8, v64, v182
	v_fmac_f32_e32 v9, v64, v183
	v_fmac_f32_e32 v6, v64, v184
	v_fmac_f32_e32 v7, v64, v185
	v_fmac_f32_e32 v4, v64, v186
	v_fmac_f32_e32 v5, v64, v187
	s_waitcnt lgkmcnt(4)
	v_fmac_f32_e32 v10, v65, v188
	v_fmac_f32_e32 v11, v65, v189
	v_fmac_f32_e32 v8, v65, v190
	v_fmac_f32_e32 v9, v65, v191
	v_fmac_f32_e32 v6, v65, v192
	v_fmac_f32_e32 v7, v65, v193
	v_fmac_f32_e32 v4, v65, v194
	v_fmac_f32_e32 v5, v65, v195
	s_waitcnt lgkmcnt(2)
	v_fmac_f32_e32 v10, v66, v196
	v_fmac_f32_e32 v11, v66, v197
	v_fmac_f32_e32 v8, v66, v198
	v_fmac_f32_e32 v9, v66, v199
	v_fmac_f32_e32 v6, v66, v200
	v_fmac_f32_e32 v7, v66, v201
	v_fmac_f32_e32 v4, v66, v202
	v_fmac_f32_e32 v5, v66, v203
	s_waitcnt lgkmcnt(0)
	v_fmac_f32_e32 v10, v67, v204
	v_fmac_f32_e32 v11, v67, v205
	v_fmac_f32_e32 v8, v67, v206
	v_fmac_f32_e32 v9, v67, v207
	v_fmac_f32_e32 v6, v67, v208
	v_fmac_f32_e32 v7, v67, v209
	v_fmac_f32_e32 v4, v67, v210
	v_fmac_f32_e32 v5, v67, v211
	s_waitcnt vmcnt(32)
	global_load_dword v52, v12, s[0:1]
	s_add_u32 s0, s0, s6
	s_addc_u32 s1, s1, 0
	global_load_dword v53, v12, s[0:1]
	s_add_u32 s0, s0, s6
	s_addc_u32 s1, s1, 0
	global_load_dword v54, v12, s[0:1]
	s_add_u32 s0, s0, s6
	s_addc_u32 s1, s1, 0
	global_load_dword v55, v12, s[0:1]
	s_add_u32 s0, s0, s6
	s_addc_u32 s1, s1, 0
	global_load_dword v56, v12, s[0:1]
	s_add_u32 s0, s0, s6
	s_addc_u32 s1, s1, 0
	global_load_dword v57, v12, s[0:1]
	s_add_u32 s0, s0, s6
	s_addc_u32 s1, s1, 0
	global_load_dword v58, v12, s[0:1]
	s_add_u32 s0, s0, s6
	s_addc_u32 s1, s1, 0
	global_load_dword v59, v12, s[0:1]
	s_add_u32 s0, s0, s6
	s_addc_u32 s1, s1, 0
	global_load_dword v60, v12, s[0:1]
	s_add_u32 s0, s0, s6
	s_addc_u32 s1, s1, 0
	global_load_dword v61, v12, s[0:1]
	s_add_u32 s0, s0, s6
	s_addc_u32 s1, s1, 0
	global_load_dword v62, v12, s[0:1]
	s_add_u32 s0, s0, s6
	s_addc_u32 s1, s1, 0
	global_load_dword v63, v12, s[0:1]
	s_add_u32 s0, s0, s6
	s_addc_u32 s1, s1, 0
	global_load_dword v64, v12, s[0:1]
	s_add_u32 s0, s0, s6
	s_addc_u32 s1, s1, 0
	global_load_dword v65, v12, s[0:1]
	s_add_u32 s0, s0, s6
	s_addc_u32 s1, s1, 0
	global_load_dword v66, v12, s[0:1]
	s_add_u32 s0, s0, s6
	s_addc_u32 s1, s1, 0
	global_load_dword v67, v12, s[0:1]
	s_add_u32 s0, s0, s6
	s_addc_u32 s1, s1, 0
	v_mov_b32_e32 v13, s12
	s_addk_i32 s12, 0x200
	ds_read_b128 v[84:87], v13
	ds_read_b128 v[88:91], v13 offset:16
	ds_read_b128 v[92:95], v13 offset:32
	ds_read_b128 v[96:99], v13 offset:48
	ds_read_b128 v[100:103], v13 offset:64
	ds_read_b128 v[104:107], v13 offset:80
	ds_read_b128 v[108:111], v13 offset:96
	ds_read_b128 v[112:115], v13 offset:112
	ds_read_b128 v[116:119], v13 offset:128
	ds_read_b128 v[120:123], v13 offset:144
	ds_read_b128 v[124:127], v13 offset:160
	ds_read_b128 v[128:131], v13 offset:176
	ds_read_b128 v[132:135], v13 offset:192
	ds_read_b128 v[136:139], v13 offset:208
	ds_read_b128 v[140:143], v13 offset:224
	ds_read_b128 v[144:147], v13 offset:240
	ds_read_b128 v[148:151], v13 offset:256
	ds_read_b128 v[152:155], v13 offset:272
	ds_read_b128 v[156:159], v13 offset:288
	ds_read_b128 v[160:163], v13 offset:304
	ds_read_b128 v[164:167], v13 offset:320
	ds_read_b128 v[168:171], v13 offset:336
	ds_read_b128 v[172:175], v13 offset:352
	ds_read_b128 v[176:179], v13 offset:368
	ds_read_b128 v[180:183], v13 offset:384
	ds_read_b128 v[184:187], v13 offset:400
	ds_read_b128 v[188:191], v13 offset:416
	ds_read_b128 v[192:195], v13 offset:432
	ds_read_b128 v[196:199], v13 offset:448
	ds_read_b128 v[200:203], v13 offset:464
	ds_read_b128 v[204:207], v13 offset:480
	ds_read_b128 v[208:211], v13 offset:496
	s_waitcnt lgkmcnt(15)
; #define LAS __attribute__((address_space(3)))
; __device__ __forceinline__ void phase_prologue(const In& in, unsigned char* ws, LAS unsigned char* lds, int tid, int wave, int lane) {
;     ...
;             for (int k0 = 0; k0 < D; k0 += 16) {
;                 float w[16];
; #pragma unroll
;                 for (int j = 0; j < 16; ++j) w[j] = W[(size_t)(k0 + j) * NMOD];
; #pragma unroll
;                 for (int j = 0; j < 16; ++j) { const f32x4 c0 = *(const LAS f32x4*)(condT + (k0 + j) * 8), c1 = *(const LAS f32x4*)(condT + (k0 + j) * 8 + 4);
;                     acc[0] += c0[0] * w[j]; acc[1] += c0[1] * w[j]; acc[2] += c0[2] * w[j]; acc[3] += c0[3] * w[j];
;                     acc[4] += c1[0] * w[j]; acc[5] += c1[1] * w[j]; acc[6] += c1[2] * w[j]; acc[7] += c1[3] * w[j]; }
	v_fmac_f32_e32 v10, v68, v84
	v_fmac_f32_e32 v11, v68, v85
	v_fmac_f32_e32 v8, v68, v86
	v_fmac_f32_e32 v9, v68, v87
	v_fmac_f32_e32 v6, v68, v88
	v_fmac_f32_e32 v7, v68, v89
	v_fmac_f32_e32 v4, v68, v90
	v_fmac_f32_e32 v5, v68, v91
	s_waitcnt lgkmcnt(15)
	v_fmac_f32_e32 v10, v69, v92
	v_fmac_f32_e32 v11, v69, v93
	v_fmac_f32_e32 v8, v69, v94
	v_fmac_f32_e32 v9, v69, v95
	v_fmac_f32_e32 v6, v69, v96
	v_fmac_f32_e32 v7, v69, v97
	v_fmac_f32_e32 v4, v69, v98
	v_fmac_f32_e32 v5, v69, v99
	s_waitcnt lgkmcnt(15)
	v_fmac_f32_e32 v10, v70, v100
	v_fmac_f32_e32 v11, v70, v101
	v_fmac_f32_e32 v8, v70, v102
	v_fmac_f32_e32 v9, v70, v103
	v_fmac_f32_e32 v6, v70, v104
	v_fmac_f32_e32 v7, v70, v105
	v_fmac_f32_e32 v4, v70, v106
	v_fmac_f32_e32 v5, v70, v107
	s_waitcnt lgkmcnt(15)
	v_fmac_f32_e32 v10, v71, v108
	v_fmac_f32_e32 v11, v71, v109
	v_fmac_f32_e32 v8, v71, v110
	v_fmac_f32_e32 v9, v71, v111
	v_fmac_f32_e32 v6, v71, v112
	v_fmac_f32_e32 v7, v71, v113
	v_fmac_f32_e32 v4, v71, v114
	v_fmac_f32_e32 v5, v71, v115
	s_waitcnt lgkmcnt(15)
	v_fmac_f32_e32 v10, v72, v116
	v_fmac_f32_e32 v11, v72, v117
	v_fmac_f32_e32 v8, v72, v118
	v_fmac_f32_e32 v9, v72, v119
	v_fmac_f32_e32 v6, v72, v120
	v_fmac_f32_e32 v7, v72, v121
	v_fmac_f32_e32 v4, v72, v122
	v_fmac_f32_e32 v5, v72, v123
	s_waitcnt lgkmcnt(15)
	v_fmac_f32_e32 v10, v73, v124
	v_fmac_f32_e32 v11, v73, v125
	v_fmac_f32_e32 v8, v73, v126
	v_fmac_f32_e32 v9, v73, v127
	v_fmac_f32_e32 v6, v73, v128
	v_fmac_f32_e32 v7, v73, v129
	v_fmac_f32_e32 v4, v73, v130
	v_fmac_f32_e32 v5, v73, v131
	s_waitcnt lgkmcnt(15)
	v_fmac_f32_e32 v10, v74, v132
	v_fmac_f32_e32 v11, v74, v133
	v_fmac_f32_e32 v8, v74, v134
	v_fmac_f32_e32 v9, v74, v135
	v_fmac_f32_e32 v6, v74, v136
	v_fmac_f32_e32 v7, v74, v137
	v_fmac_f32_e32 v4, v74, v138
	v_fmac_f32_e32 v5, v74, v139
	s_waitcnt lgkmcnt(15)
	v_fmac_f32_e32 v10, v75, v140
	v_fmac_f32_e32 v11, v75, v141
	v_fmac_f32_e32 v8, v75, v142
	v_fmac_f32_e32 v9, v75, v143
	v_fmac_f32_e32 v6, v75, v144
	v_fmac_f32_e32 v7, v75, v145
	v_fmac_f32_e32 v4, v75, v146
	v_fmac_f32_e32 v5, v75, v147
	s_waitcnt lgkmcnt(14)
	v_fmac_f32_e32 v10, v76, v148
	v_fmac_f32_e32 v11, v76, v149
	v_fmac_f32_e32 v8, v76, v150
	v_fmac_f32_e32 v9, v76, v151
	v_fmac_f32_e32 v6, v76, v152
	v_fmac_f32_e32 v7, v76, v153
	v_fmac_f32_e32 v4, v76, v154
	v_fmac_f32_e32 v5, v76, v155
	s_waitcnt lgkmcnt(12)
	v_fmac_f32_e32 v10, v77, v156
	v_fmac_f32_e32 v11, v77, v157
	v_fmac_f32_e32 v8, v77, v158
	v_fmac_f32_e32 v9, v77, v159
	v_fmac_f32_e32 v6, v77, v160
	v_fmac_f32_e32 v7, v77, v161
	v_fmac_f32_e32 v4, v77, v162
	v_fmac_f32_e32 v5, v77, v163
	s_waitcnt lgkmcnt(10)
	v_fmac_f32_e32 v10, v78, v164
	v_fmac_f32_e32 v11, v78, v165
	v_fmac_f32_e32 v8, v78, v166
	v_fmac_f32_e32 v9, v78, v167
	v_fmac_f32_e32 v6, v78, v168
	v_fmac_f32_e32 v7, v78, v169
	v_fmac_f32_e32 v4, v78, v170
	v_fmac_f32_e32 v5, v78, v171
	s_waitcnt lgkmcnt(8)
	v_fmac_f32_e32 v10, v79, v172
	v_fmac_f32_e32 v11, v79, v173
	v_fmac_f32_e32 v8, v79, v174
	v_fmac_f32_e32 v9, v79, v175
	v_fmac_f32_e32 v6, v79, v176
	v_fmac_f32_e32 v7, v79, v177
	v_fmac_f32_e32 v4, v79, v178
	v_fmac_f32_e32 v5, v79, v179
	s_waitcnt lgkmcnt(6)
	v_fmac_f32_e32 v10, v80, v180
	v_fmac_f32_e32 v11, v80, v181
	v_fmac_f32_e32 v8, v80, v182
	v_fmac_f32_e32 v9, v80, v183
	v_fmac_f32_e32 v6, v80, v184
	v_fmac_f32_e32 v7, v80, v185
	v_fmac_f32_e32 v4, v80, v186
	v_fmac_f32_e32 v5, v80, v187
	s_waitcnt lgkmcnt(4)
	v_fmac_f32_e32 v10, v81, v188
	v_fmac_f32_e32 v11, v81, v189
	v_fmac_f32_e32 v8, v81, v190
	v_fmac_f32_e32 v9, v81, v191
	v_fmac_f32_e32 v6, v81, v192
	v_fmac_f32_e32 v7, v81, v193
	v_fmac_f32_e32 v4, v81, v194
	v_fmac_f32_e32 v5, v81, v195
	s_waitcnt lgkmcnt(2)
	v_fmac_f32_e32 v10, v82, v196
	v_fmac_f32_e32 v11, v82, v197
	v_fmac_f32_e32 v8, v82, v198
	v_fmac_f32_e32 v9, v82, v199
	v_fmac_f32_e32 v6, v82, v200
	v_fmac_f32_e32 v7, v82, v201
	v_fmac_f32_e32 v4, v82, v202
	v_fmac_f32_e32 v5, v82, v203
	s_waitcnt lgkmcnt(0)
	v_fmac_f32_e32 v10, v83, v204
	v_fmac_f32_e32 v11, v83, v205
	v_fmac_f32_e32 v8, v83, v206
	v_fmac_f32_e32 v9, v83, v207
	v_fmac_f32_e32 v6, v83, v208
	v_fmac_f32_e32 v7, v83, v209
	v_fmac_f32_e32 v4, v83, v210
	v_fmac_f32_e32 v5, v83, v211
	s_sub_i32 s11, s11, 1
	s_cmp_lg_u32 s11, 0
	s_cbranch_scc1 .Lada_loop
; #define LAS __attribute__((address_space(3)))
; __device__ __forceinline__ void phase_prologue(const In& in, unsigned char* ws, LAS unsigned char* lds, int tid, int wave, int lane) {
;     ...
;             for (int k0 = 0; k0 < D; k0 += 16) {
;                 float w[16];
; #pragma unroll
;                 for (int j = 0; j < 16; ++j) w[j] = W[(size_t)(k0 + j) * NMOD];
; #pragma unroll
;                 for (int j = 0; j < 16; ++j) { const f32x4 c0 = *(const LAS f32x4*)(condT + (k0 + j) * 8), c1 = *(const LAS f32x4*)(condT + (k0 + j) * 8 + 4);
;                     acc[0] += c0[0] * w[j]; acc[1] += c0[1] * w[j]; acc[2] += c0[2] * w[j]; acc[3] += c0[3] * w[j];
;                     acc[4] += c1[0] * w[j]; acc[5] += c1[1] * w[j]; acc[6] += c1[2] * w[j]; acc[7] += c1[3] * w[j]; }
	s_waitcnt vmcnt(32)
	global_load_dword v68, v12, s[0:1]
	s_add_u32 s0, s0, s6
	s_addc_u32 s1, s1, 0
	global_load_dword v69, v12, s[0:1]
	s_add_u32 s0, s0, s6
	s_addc_u32 s1, s1, 0
	global_load_dword v70, v12, s[0:1]
	s_add_u32 s0, s0, s6
	s_addc_u32 s1, s1, 0
	global_load_dword v71, v12, s[0:1]
	s_add_u32 s0, s0, s6
	s_addc_u32 s1, s1, 0
	global_load_dword v72, v12, s[0:1]
	s_add_u32 s0, s0, s6
	s_addc_u32 s1, s1, 0
	global_load_dword v73, v12, s[0:1]
	s_add_u32 s0, s0, s6
	s_addc_u32 s1, s1, 0
	global_load_dword v74, v12, s[0:1]
	s_add_u32 s0, s0, s6
	s_addc_u32 s1, s1, 0
	global_load_dword v75, v12, s[0:1]
	s_add_u32 s0, s0, s6
	s_addc_u32 s1, s1, 0
	global_load_dword v76, v12, s[0:1]
	s_add_u32 s0, s0, s6
	s_addc_u32 s1, s1, 0
	global_load_dword v77, v12, s[0:1]
	s_add_u32 s0, s0, s6
	s_addc_u32 s1, s1, 0
	global_load_dword v78, v12, s[0:1]
	s_add_u32 s0, s0, s6
	s_addc_u32 s1, s1, 0
	global_load_dword v79, v12, s[0:1]
	s_add_u32 s0, s0, s6
	s_addc_u32 s1, s1, 0
	global_load_dword v80, v12, s[0:1]
	s_add_u32 s0, s0, s6
	s_addc_u32 s1, s1, 0
	global_load_dword v81, v12, s[0:1]
	s_add_u32 s0, s0, s6
	s_addc_u32 s1, s1, 0
	global_load_dword v82, v12, s[0:1]
	s_add_u32 s0, s0, s6
	s_addc_u32 s1, s1, 0
	global_load_dword v83, v12, s[0:1]
	s_add_u32 s0, s0, s6
	s_addc_u32 s1, s1, 0
	v_mov_b32_e32 v13, s12
	s_addk_i32 s12, 0x200
	ds_read_b128 v[84:87], v13
	ds_read_b128 v[88:91], v13 offset:16
	ds_read_b128 v[92:95], v13 offset:32
	ds_read_b128 v[96:99], v13 offset:48
	ds_read_b128 v[100:103], v13 offset:64
	ds_read_b128 v[104:107], v13 offset:80
	ds_read_b128 v[108:111], v13 offset:96
	ds_read_b128 v[112:115], v13 offset:112
	ds_read_b128 v[116:119], v13 offset:128
	ds_read_b128 v[120:123], v13 offset:144
	ds_read_b128 v[124:127], v13 offset:160
	ds_read_b128 v[128:131], v13 offset:176
	ds_read_b128 v[132:135], v13 offset:192
	ds_read_b128 v[136:139], v13 offset:208
	ds_read_b128 v[140:143], v13 offset:224
	ds_read_b128 v[144:147], v13 offset:240
	ds_read_b128 v[148:151], v13 offset:256
	ds_read_b128 v[152:155], v13 offset:272
	ds_read_b128 v[156:159], v13 offset:288
	ds_read_b128 v[160:163], v13 offset:304
	ds_read_b128 v[164:167], v13 offset:320
	ds_read_b128 v[168:171], v13 offset:336
	ds_read_b128 v[172:175], v13 offset:352
	ds_read_b128 v[176:179], v13 offset:368
	ds_read_b128 v[180:183], v13 offset:384
	ds_read_b128 v[184:187], v13 offset:400
	ds_read_b128 v[188:191], v13 offset:416
	ds_read_b128 v[192:195], v13 offset:432
	ds_read_b128 v[196:199], v13 offset:448
	ds_read_b128 v[200:203], v13 offset:464
	ds_read_b128 v[204:207], v13 offset:480
	ds_read_b128 v[208:211], v13 offset:496
	s_waitcnt lgkmcnt(15)
	v_fmac_f32_e32 v10, v20, v84
	v_fmac_f32_e32 v11, v20, v85
	v_fmac_f32_e32 v8, v20, v86
	v_fmac_f32_e32 v9, v20, v87
	v_fmac_f32_e32 v6, v20, v88
	v_fmac_f32_e32 v7, v20, v89
	v_fmac_f32_e32 v4, v20, v90
	v_fmac_f32_e32 v5, v20, v91
	s_waitcnt lgkmcnt(15)
	v_fmac_f32_e32 v10, v21, v92
	v_fmac_f32_e32 v11, v21, v93
	v_fmac_f32_e32 v8, v21, v94
	v_fmac_f32_e32 v9, v21, v95
	v_fmac_f32_e32 v6, v21, v96
	v_fmac_f32_e32 v7, v21, v97
	v_fmac_f32_e32 v4, v21, v98
	v_fmac_f32_e32 v5, v21, v99
	s_waitcnt lgkmcnt(15)
	v_fmac_f32_e32 v10, v22, v100
	v_fmac_f32_e32 v11, v22, v101
	v_fmac_f32_e32 v8, v22, v102
	v_fmac_f32_e32 v9, v22, v103
	v_fmac_f32_e32 v6, v22, v104
	v_fmac_f32_e32 v7, v22, v105
	v_fmac_f32_e32 v4, v22, v106
	v_fmac_f32_e32 v5, v22, v107
	s_waitcnt lgkmcnt(15)
	v_fmac_f32_e32 v10, v23, v108
	v_fmac_f32_e32 v11, v23, v109
	v_fmac_f32_e32 v8, v23, v110
	v_fmac_f32_e32 v9, v23, v111
	v_fmac_f32_e32 v6, v23, v112
	v_fmac_f32_e32 v7, v23, v113
	v_fmac_f32_e32 v4, v23, v114
	v_fmac_f32_e32 v5, v23, v115
	s_waitcnt lgkmcnt(15)
	v_fmac_f32_e32 v10, v24, v116
	v_fmac_f32_e32 v11, v24, v117
	v_fmac_f32_e32 v8, v24, v118
	v_fmac_f32_e32 v9, v24, v119
	v_fmac_f32_e32 v6, v24, v120
	v_fmac_f32_e32 v7, v24, v121
	v_fmac_f32_e32 v4, v24, v122
	v_fmac_f32_e32 v5, v24, v123
	s_waitcnt lgkmcnt(15)
	v_fmac_f32_e32 v10, v25, v124
	v_fmac_f32_e32 v11, v25, v125
	v_fmac_f32_e32 v8, v25, v126
	v_fmac_f32_e32 v9, v25, v127
	v_fmac_f32_e32 v6, v25, v128
	v_fmac_f32_e32 v7, v25, v129
	v_fmac_f32_e32 v4, v25, v130
	v_fmac_f32_e32 v5, v25, v131
	s_waitcnt lgkmcnt(15)
	v_fmac_f32_e32 v10, v26, v132
	v_fmac_f32_e32 v11, v26, v133
	v_fmac_f32_e32 v8, v26, v134
	v_fmac_f32_e32 v9, v26, v135
	v_fmac_f32_e32 v6, v26, v136
	v_fmac_f32_e32 v7, v26, v137
	v_fmac_f32_e32 v4, v26, v138
	v_fmac_f32_e32 v5, v26, v139
	s_waitcnt lgkmcnt(15)
	v_fmac_f32_e32 v10, v27, v140
	v_fmac_f32_e32 v11, v27, v141
	v_fmac_f32_e32 v8, v27, v142
	v_fmac_f32_e32 v9, v27, v143
	v_fmac_f32_e32 v6, v27, v144
	v_fmac_f32_e32 v7, v27, v145
	v_fmac_f32_e32 v4, v27, v146
	v_fmac_f32_e32 v5, v27, v147
	s_waitcnt lgkmcnt(14)
	v_fmac_f32_e32 v10, v28, v148
	v_fmac_f32_e32 v11, v28, v149
	v_fmac_f32_e32 v8, v28, v150
	v_fmac_f32_e32 v9, v28, v151
	v_fmac_f32_e32 v6, v28, v152
	v_fmac_f32_e32 v7, v28, v153
	v_fmac_f32_e32 v4, v28, v154
	v_fmac_f32_e32 v5, v28, v155
	s_waitcnt lgkmcnt(12)
	v_fmac_f32_e32 v10, v29, v156
	v_fmac_f32_e32 v11, v29, v157
	v_fmac_f32_e32 v8, v29, v158
	v_fmac_f32_e32 v9, v29, v159
	v_fmac_f32_e32 v6, v29, v160
	v_fmac_f32_e32 v7, v29, v161
	v_fmac_f32_e32 v4, v29, v162
	v_fmac_f32_e32 v5, v29, v163
	s_waitcnt lgkmcnt(10)
	v_fmac_f32_e32 v10, v30, v164
	v_fmac_f32_e32 v11, v30, v165
	v_fmac_f32_e32 v8, v30, v166
	v_fmac_f32_e32 v9, v30, v167
	v_fmac_f32_e32 v6, v30, v168
	v_fmac_f32_e32 v7, v30, v169
	v_fmac_f32_e32 v4, v30, v170
	v_fmac_f32_e32 v5, v30, v171
	s_waitcnt lgkmcnt(8)
; #define LAS __attribute__((address_space(3)))
; __device__ __forceinline__ void phase_prologue(const In& in, unsigned char* ws, LAS unsigned char* lds, int tid, int wave, int lane) {
;     ...
;             for (int k0 = 0; k0 < D; k0 += 16) {
;                 float w[16];
; #pragma unroll
;                 for (int j = 0; j < 16; ++j) w[j] = W[(size_t)(k0 + j) * NMOD];
; #pragma unroll
;                 for (int j = 0; j < 16; ++j) { const f32x4 c0 = *(const LAS f32x4*)(condT + (k0 + j) * 8), c1 = *(const LAS f32x4*)(condT + (k0 + j) * 8 + 4);
;                     acc[0] += c0[0] * w[j]; acc[1] += c0[1] * w[j]; acc[2] += c0[2] * w[j]; acc[3] += c0[3] * w[j];
;                     acc[4] += c1[0] * w[j]; acc[5] += c1[1] * w[j]; acc[6] += c1[2] * w[j]; acc[7] += c1[3] * w[j]; }
	v_fmac_f32_e32 v10, v31, v172
	v_fmac_f32_e32 v11, v31, v173
	v_fmac_f32_e32 v8, v31, v174
	v_fmac_f32_e32 v9, v31, v175
	v_fmac_f32_e32 v6, v31, v176
	v_fmac_f32_e32 v7, v31, v177
	v_fmac_f32_e32 v4, v31, v178
	v_fmac_f32_e32 v5, v31, v179
	s_waitcnt lgkmcnt(6)
	v_fmac_f32_e32 v10, v32, v180
	v_fmac_f32_e32 v11, v32, v181
	v_fmac_f32_e32 v8, v32, v182
	v_fmac_f32_e32 v9, v32, v183
	v_fmac_f32_e32 v6, v32, v184
	v_fmac_f32_e32 v7, v32, v185
	v_fmac_f32_e32 v4, v32, v186
	v_fmac_f32_e32 v5, v32, v187
	s_waitcnt lgkmcnt(4)
	v_fmac_f32_e32 v10, v33, v188
	v_fmac_f32_e32 v11, v33, v189
	v_fmac_f32_e32 v8, v33, v190
	v_fmac_f32_e32 v9, v33, v191
	v_fmac_f32_e32 v6, v33, v192
	v_fmac_f32_e32 v7, v33, v193
	v_fmac_f32_e32 v4, v33, v194
	v_fmac_f32_e32 v5, v33, v195
	s_waitcnt lgkmcnt(2)
	v_fmac_f32_e32 v10, v34, v196
	v_fmac_f32_e32 v11, v34, v197
	v_fmac_f32_e32 v8, v34, v198
	v_fmac_f32_e32 v9, v34, v199
	v_fmac_f32_e32 v6, v34, v200
	v_fmac_f32_e32 v7, v34, v201
	v_fmac_f32_e32 v4, v34, v202
	v_fmac_f32_e32 v5, v34, v203
	s_waitcnt lgkmcnt(0)
	v_fmac_f32_e32 v10, v35, v204
	v_fmac_f32_e32 v11, v35, v205
	v_fmac_f32_e32 v8, v35, v206
	v_fmac_f32_e32 v9, v35, v207
	v_fmac_f32_e32 v6, v35, v208
	v_fmac_f32_e32 v7, v35, v209
	v_fmac_f32_e32 v4, v35, v210
	v_fmac_f32_e32 v5, v35, v211
	s_waitcnt vmcnt(32)
	v_mov_b32_e32 v13, s12
	s_addk_i32 s12, 0x200
	ds_read_b128 v[84:87], v13
	ds_read_b128 v[88:91], v13 offset:16
	ds_read_b128 v[92:95], v13 offset:32
	ds_read_b128 v[96:99], v13 offset:48
	ds_read_b128 v[100:103], v13 offset:64
	ds_read_b128 v[104:107], v13 offset:80
	ds_read_b128 v[108:111], v13 offset:96
	ds_read_b128 v[112:115], v13 offset:112
	ds_read_b128 v[116:119], v13 offset:128
	ds_read_b128 v[120:123], v13 offset:144
	ds_read_b128 v[124:127], v13 offset:160
	ds_read_b128 v[128:131], v13 offset:176
	ds_read_b128 v[132:135], v13 offset:192
	ds_read_b128 v[136:139], v13 offset:208
	ds_read_b128 v[140:143], v13 offset:224
	ds_read_b128 v[144:147], v13 offset:240
	ds_read_b128 v[148:151], v13 offset:256
	ds_read_b128 v[152:155], v13 offset:272
	ds_read_b128 v[156:159], v13 offset:288
	ds_read_b128 v[160:163], v13 offset:304
	ds_read_b128 v[164:167], v13 offset:320
	ds_read_b128 v[168:171], v13 offset:336
	ds_read_b128 v[172:175], v13 offset:352
	ds_read_b128 v[176:179], v13 offset:368
	ds_read_b128 v[180:183], v13 offset:384
	ds_read_b128 v[184:187], v13 offset:400
	ds_read_b128 v[188:191], v13 offset:416
	ds_read_b128 v[192:195], v13 offset:432
	ds_read_b128 v[196:199], v13 offset:448
	ds_read_b128 v[200:203], v13 offset:464
	ds_read_b128 v[204:207], v13 offset:480
	ds_read_b128 v[208:211], v13 offset:496
	s_waitcnt lgkmcnt(15)
	v_fmac_f32_e32 v10, v36, v84
	v_fmac_f32_e32 v11, v36, v85
	v_fmac_f32_e32 v8, v36, v86
	v_fmac_f32_e32 v9, v36, v87
	v_fmac_f32_e32 v6, v36, v88
	v_fmac_f32_e32 v7, v36, v89
	v_fmac_f32_e32 v4, v36, v90
	v_fmac_f32_e32 v5, v36, v91
	s_waitcnt lgkmcnt(15)
	v_fmac_f32_e32 v10, v37, v92
	v_fmac_f32_e32 v11, v37, v93
	v_fmac_f32_e32 v8, v37, v94
	v_fmac_f32_e32 v9, v37, v95
	v_fmac_f32_e32 v6, v37, v96
	v_fmac_f32_e32 v7, v37, v97
	v_fmac_f32_e32 v4, v37, v98
	v_fmac_f32_e32 v5, v37, v99
	s_waitcnt lgkmcnt(15)
	v_fmac_f32_e32 v10, v38, v100
	v_fmac_f32_e32 v11, v38, v101
	v_fmac_f32_e32 v8, v38, v102
	v_fmac_f32_e32 v9, v38, v103
	v_fmac_f32_e32 v6, v38, v104
	v_fmac_f32_e32 v7, v38, v105
	v_fmac_f32_e32 v4, v38, v106
	v_fmac_f32_e32 v5, v38, v107
	s_waitcnt lgkmcnt(15)
	v_fmac_f32_e32 v10, v39, v108
	v_fmac_f32_e32 v11, v39, v109
	v_fmac_f32_e32 v8, v39, v110
	v_fmac_f32_e32 v9, v39, v111
	v_fmac_f32_e32 v6, v39, v112
	v_fmac_f32_e32 v7, v39, v113
	v_fmac_f32_e32 v4, v39, v114
	v_fmac_f32_e32 v5, v39, v115
	s_waitcnt lgkmcnt(15)
	v_fmac_f32_e32 v10, v40, v116
	v_fmac_f32_e32 v11, v40, v117
	v_fmac_f32_e32 v8, v40, v118
	v_fmac_f32_e32 v9, v40, v119
	v_fmac_f32_e32 v6, v40, v120
	v_fmac_f32_e32 v7, v40, v121
	v_fmac_f32_e32 v4, v40, v122
	v_fmac_f32_e32 v5, v40, v123
	s_waitcnt lgkmcnt(15)
	v_fmac_f32_e32 v10, v41, v124
	v_fmac_f32_e32 v11, v41, v125
	v_fmac_f32_e32 v8, v41, v126
	v_fmac_f32_e32 v9, v41, v127
	v_fmac_f32_e32 v6, v41, v128
	v_fmac_f32_e32 v7, v41, v129
	v_fmac_f32_e32 v4, v41, v130
	v_fmac_f32_e32 v5, v41, v131
	s_waitcnt lgkmcnt(15)
	v_fmac_f32_e32 v10, v42, v132
	v_fmac_f32_e32 v11, v42, v133
	v_fmac_f32_e32 v8, v42, v134
	v_fmac_f32_e32 v9, v42, v135
	v_fmac_f32_e32 v6, v42, v136
	v_fmac_f32_e32 v7, v42, v137
	v_fmac_f32_e32 v4, v42, v138
	v_fmac_f32_e32 v5, v42, v139
	s_waitcnt lgkmcnt(15)
	v_fmac_f32_e32 v10, v43, v140
	v_fmac_f32_e32 v11, v43, v141
	v_fmac_f32_e32 v8, v43, v142
	v_fmac_f32_e32 v9, v43, v143
	v_fmac_f32_e32 v6, v43, v144
	v_fmac_f32_e32 v7, v43, v145
	v_fmac_f32_e32 v4, v43, v146
	v_fmac_f32_e32 v5, v43, v147
	s_waitcnt lgkmcnt(14)
	v_fmac_f32_e32 v10, v44, v148
	v_fmac_f32_e32 v11, v44, v149
	v_fmac_f32_e32 v8, v44, v150
	v_fmac_f32_e32 v9, v44, v151
	v_fmac_f32_e32 v6, v44, v152
	v_fmac_f32_e32 v7, v44, v153
	v_fmac_f32_e32 v4, v44, v154
	v_fmac_f32_e32 v5, v44, v155
	s_waitcnt lgkmcnt(12)
	v_fmac_f32_e32 v10, v45, v156
	v_fmac_f32_e32 v11, v45, v157
	v_fmac_f32_e32 v8, v45, v158
	v_fmac_f32_e32 v9, v45, v159
	v_fmac_f32_e32 v6, v45, v160
	v_fmac_f32_e32 v7, v45, v161
	v_fmac_f32_e32 v4, v45, v162
	v_fmac_f32_e32 v5, v45, v163
	s_waitcnt lgkmcnt(10)
	v_fmac_f32_e32 v10, v46, v164
	v_fmac_f32_e32 v11, v46, v165
	v_fmac_f32_e32 v8, v46, v166
	v_fmac_f32_e32 v9, v46, v167
	v_fmac_f32_e32 v6, v46, v168
	v_fmac_f32_e32 v7, v46, v169
	v_fmac_f32_e32 v4, v46, v170
	v_fmac_f32_e32 v5, v46, v171
	s_waitcnt lgkmcnt(8)
; #define LAS __attribute__((address_space(3)))
; __device__ __forceinline__ void phase_prologue(const In& in, unsigned char* ws, LAS unsigned char* lds, int tid, int wave, int lane) {
;     ...
;             for (int k0 = 0; k0 < D; k0 += 16) {
;                 float w[16];
; #pragma unroll
;                 for (int j = 0; j < 16; ++j) w[j] = W[(size_t)(k0 + j) * NMOD];
; #pragma unroll
;                 for (int j = 0; j < 16; ++j) { const f32x4 c0 = *(const LAS f32x4*)(condT + (k0 + j) * 8), c1 = *(const LAS f32x4*)(condT + (k0 + j) * 8 + 4);
;                     acc[0] += c0[0] * w[j]; acc[1] += c0[1] * w[j]; acc[2] += c0[2] * w[j]; acc[3] += c0[3] * w[j];
;                     acc[4] += c1[0] * w[j]; acc[5] += c1[1] * w[j]; acc[6] += c1[2] * w[j]; acc[7] += c1[3] * w[j]; }
	v_fmac_f32_e32 v10, v47, v172
	v_fmac_f32_e32 v11, v47, v173
	v_fmac_f32_e32 v8, v47, v174
	v_fmac_f32_e32 v9, v47, v175
	v_fmac_f32_e32 v6, v47, v176
	v_fmac_f32_e32 v7, v47, v177
	v_fmac_f32_e32 v4, v47, v178
	v_fmac_f32_e32 v5, v47, v179
	s_waitcnt lgkmcnt(6)
	v_fmac_f32_e32 v10, v48, v180
	v_fmac_f32_e32 v11, v48, v181
	v_fmac_f32_e32 v8, v48, v182
	v_fmac_f32_e32 v9, v48, v183
	v_fmac_f32_e32 v6, v48, v184
	v_fmac_f32_e32 v7, v48, v185
	v_fmac_f32_e32 v4, v48, v186
	v_fmac_f32_e32 v5, v48, v187
	s_waitcnt lgkmcnt(4)
	v_fmac_f32_e32 v10, v49, v188
	v_fmac_f32_e32 v11, v49, v189
	v_fmac_f32_e32 v8, v49, v190
	v_fmac_f32_e32 v9, v49, v191
	v_fmac_f32_e32 v6, v49, v192
	v_fmac_f32_e32 v7, v49, v193
	v_fmac_f32_e32 v4, v49, v194
	v_fmac_f32_e32 v5, v49, v195
	s_waitcnt lgkmcnt(2)
	v_fmac_f32_e32 v10, v50, v196
	v_fmac_f32_e32 v11, v50, v197
	v_fmac_f32_e32 v8, v50, v198
	v_fmac_f32_e32 v9, v50, v199
	v_fmac_f32_e32 v6, v50, v200
	v_fmac_f32_e32 v7, v50, v201
	v_fmac_f32_e32 v4, v50, v202
	v_fmac_f32_e32 v5, v50, v203
	s_waitcnt lgkmcnt(0)
	v_fmac_f32_e32 v10, v51, v204
	v_fmac_f32_e32 v11, v51, v205
	v_fmac_f32_e32 v8, v51, v206
	v_fmac_f32_e32 v9, v51, v207
	v_fmac_f32_e32 v6, v51, v208
	v_fmac_f32_e32 v7, v51, v209
	v_fmac_f32_e32 v4, v51, v210
	v_fmac_f32_e32 v5, v51, v211
	s_waitcnt vmcnt(16)
	v_mov_b32_e32 v13, s12
	s_addk_i32 s12, 0x200
	ds_read_b128 v[84:87], v13
	ds_read_b128 v[88:91], v13 offset:16
	ds_read_b128 v[92:95], v13 offset:32
	ds_read_b128 v[96:99], v13 offset:48
	ds_read_b128 v[100:103], v13 offset:64
	ds_read_b128 v[104:107], v13 offset:80
	ds_read_b128 v[108:111], v13 offset:96
	ds_read_b128 v[112:115], v13 offset:112
	ds_read_b128 v[116:119], v13 offset:128
	ds_read_b128 v[120:123], v13 offset:144
	ds_read_b128 v[124:127], v13 offset:160
	ds_read_b128 v[128:131], v13 offset:176
	ds_read_b128 v[132:135], v13 offset:192
	ds_read_b128 v[136:139], v13 offset:208
	ds_read_b128 v[140:143], v13 offset:224
	ds_read_b128 v[144:147], v13 offset:240
	ds_read_b128 v[148:151], v13 offset:256
	ds_read_b128 v[152:155], v13 offset:272
	ds_read_b128 v[156:159], v13 offset:288
	ds_read_b128 v[160:163], v13 offset:304
	ds_read_b128 v[164:167], v13 offset:320
	ds_read_b128 v[168:171], v13 offset:336
	ds_read_b128 v[172:175], v13 offset:352
	ds_read_b128 v[176:179], v13 offset:368
	ds_read_b128 v[180:183], v13 offset:384
	ds_read_b128 v[184:187], v13 offset:400
	ds_read_b128 v[188:191], v13 offset:416
	ds_read_b128 v[192:195], v13 offset:432
	ds_read_b128 v[196:199], v13 offset:448
	ds_read_b128 v[200:203], v13 offset:464
	ds_read_b128 v[204:207], v13 offset:480
	ds_read_b128 v[208:211], v13 offset:496
	s_waitcnt lgkmcnt(15)
	v_fmac_f32_e32 v10, v52, v84
	v_fmac_f32_e32 v11, v52, v85
	v_fmac_f32_e32 v8, v52, v86
	v_fmac_f32_e32 v9, v52, v87
	v_fmac_f32_e32 v6, v52, v88
	v_fmac_f32_e32 v7, v52, v89
	v_fmac_f32_e32 v4, v52, v90
	v_fmac_f32_e32 v5, v52, v91
	s_waitcnt lgkmcnt(15)
	v_fmac_f32_e32 v10, v53, v92
	v_fmac_f32_e32 v11, v53, v93
	v_fmac_f32_e32 v8, v53, v94
	v_fmac_f32_e32 v9, v53, v95
	v_fmac_f32_e32 v6, v53, v96
	v_fmac_f32_e32 v7, v53, v97
	v_fmac_f32_e32 v4, v53, v98
	v_fmac_f32_e32 v5, v53, v99
	s_waitcnt lgkmcnt(15)
	v_fmac_f32_e32 v10, v54, v100
	v_fmac_f32_e32 v11, v54, v101
	v_fmac_f32_e32 v8, v54, v102
	v_fmac_f32_e32 v9, v54, v103
	v_fmac_f32_e32 v6, v54, v104
	v_fmac_f32_e32 v7, v54, v105
	v_fmac_f32_e32 v4, v54, v106
	v_fmac_f32_e32 v5, v54, v107
	s_waitcnt lgkmcnt(15)
	v_fmac_f32_e32 v10, v55, v108
	v_fmac_f32_e32 v11, v55, v109
	v_fmac_f32_e32 v8, v55, v110
	v_fmac_f32_e32 v9, v55, v111
	v_fmac_f32_e32 v6, v55, v112
	v_fmac_f32_e32 v7, v55, v113
	v_fmac_f32_e32 v4, v55, v114
	v_fmac_f32_e32 v5, v55, v115
	s_waitcnt lgkmcnt(15)
	v_fmac_f32_e32 v10, v56, v116
	v_fmac_f32_e32 v11, v56, v117
	v_fmac_f32_e32 v8, v56, v118
	v_fmac_f32_e32 v9, v56, v119
	v_fmac_f32_e32 v6, v56, v120
	v_fmac_f32_e32 v7, v56, v121
	v_fmac_f32_e32 v4, v56, v122
	v_fmac_f32_e32 v5, v56, v123
	s_waitcnt lgkmcnt(15)
	v_fmac_f32_e32 v10, v57, v124
	v_fmac_f32_e32 v11, v57, v125
	v_fmac_f32_e32 v8, v57, v126
	v_fmac_f32_e32 v9, v57, v127
	v_fmac_f32_e32 v6, v57, v128
	v_fmac_f32_e32 v7, v57, v129
	v_fmac_f32_e32 v4, v57, v130
	v_fmac_f32_e32 v5, v57, v131
	s_waitcnt lgkmcnt(15)
	v_fmac_f32_e32 v10, v58, v132
	v_fmac_f32_e32 v11, v58, v133
	v_fmac_f32_e32 v8, v58, v134
	v_fmac_f32_e32 v9, v58, v135
	v_fmac_f32_e32 v6, v58, v136
	v_fmac_f32_e32 v7, v58, v137
	v_fmac_f32_e32 v4, v58, v138
	v_fmac_f32_e32 v5, v58, v139
	s_waitcnt lgkmcnt(15)
	v_fmac_f32_e32 v10, v59, v140
	v_fmac_f32_e32 v11, v59, v141
	v_fmac_f32_e32 v8, v59, v142
	v_fmac_f32_e32 v9, v59, v143
	v_fmac_f32_e32 v6, v59, v144
	v_fmac_f32_e32 v7, v59, v145
	v_fmac_f32_e32 v4, v59, v146
	v_fmac_f32_e32 v5, v59, v147
	s_waitcnt lgkmcnt(14)
	v_fmac_f32_e32 v10, v60, v148
	v_fmac_f32_e32 v11, v60, v149
	v_fmac_f32_e32 v8, v60, v150
	v_fmac_f32_e32 v9, v60, v151
	v_fmac_f32_e32 v6, v60, v152
	v_fmac_f32_e32 v7, v60, v153
	v_fmac_f32_e32 v4, v60, v154
	v_fmac_f32_e32 v5, v60, v155
	s_waitcnt lgkmcnt(12)
	v_fmac_f32_e32 v10, v61, v156
	v_fmac_f32_e32 v11, v61, v157
	v_fmac_f32_e32 v8, v61, v158
	v_fmac_f32_e32 v9, v61, v159
	v_fmac_f32_e32 v6, v61, v160
	v_fmac_f32_e32 v7, v61, v161
	v_fmac_f32_e32 v4, v61, v162
	v_fmac_f32_e32 v5, v61, v163
	s_waitcnt lgkmcnt(10)
	v_fmac_f32_e32 v10, v62, v164
	v_fmac_f32_e32 v11, v62, v165
	v_fmac_f32_e32 v8, v62, v166
	v_fmac_f32_e32 v9, v62, v167
	v_fmac_f32_e32 v6, v62, v168
	v_fmac_f32_e32 v7, v62, v169
	v_fmac_f32_e32 v4, v62, v170
	v_fmac_f32_e32 v5, v62, v171
	s_waitcnt lgkmcnt(8)
; #define LAS __attribute__((address_space(3)))
; __device__ __forceinline__ void phase_prologue(const In& in, unsigned char* ws, LAS unsigned char* lds, int tid, int wave, int lane) {
;     ...
;             for (int k0 = 0; k0 < D; k0 += 16) {
;                 float w[16];
; #pragma unroll
;                 for (int j = 0; j < 16; ++j) w[j] = W[(size_t)(k0 + j) * NMOD];
; #pragma unroll
;                 for (int j = 0; j < 16; ++j) { const f32x4 c0 = *(const LAS f32x4*)(condT + (k0 + j) * 8), c1 = *(const LAS f32x4*)(condT + (k0 + j) * 8 + 4);
;                     acc[0] += c0[0] * w[j]; acc[1] += c0[1] * w[j]; acc[2] += c0[2] * w[j]; acc[3] += c0[3] * w[j];
;                     acc[4] += c1[0] * w[j]; acc[5] += c1[1] * w[j]; acc[6] += c1[2] * w[j]; acc[7] += c1[3] * w[j]; }
	v_fmac_f32_e32 v10, v63, v172
	v_fmac_f32_e32 v11, v63, v173
	v_fmac_f32_e32 v8, v63, v174
	v_fmac_f32_e32 v9, v63, v175
	v_fmac_f32_e32 v6, v63, v176
	v_fmac_f32_e32 v7, v63, v177
	v_fmac_f32_e32 v4, v63, v178
	v_fmac_f32_e32 v5, v63, v179
	s_waitcnt lgkmcnt(6)
	v_fmac_f32_e32 v10, v64, v180
	v_fmac_f32_e32 v11, v64, v181
	v_fmac_f32_e32 v8, v64, v182
	v_fmac_f32_e32 v9, v64, v183
	v_fmac_f32_e32 v6, v64, v184
	v_fmac_f32_e32 v7, v64, v185
	v_fmac_f32_e32 v4, v64, v186
	v_fmac_f32_e32 v5, v64, v187
	s_waitcnt lgkmcnt(4)
	v_fmac_f32_e32 v10, v65, v188
	v_fmac_f32_e32 v11, v65, v189
	v_fmac_f32_e32 v8, v65, v190
	v_fmac_f32_e32 v9, v65, v191
	v_fmac_f32_e32 v6, v65, v192
	v_fmac_f32_e32 v7, v65, v193
	v_fmac_f32_e32 v4, v65, v194
	v_fmac_f32_e32 v5, v65, v195
	s_waitcnt lgkmcnt(2)
	v_fmac_f32_e32 v10, v66, v196
	v_fmac_f32_e32 v11, v66, v197
	v_fmac_f32_e32 v8, v66, v198
	v_fmac_f32_e32 v9, v66, v199
	v_fmac_f32_e32 v6, v66, v200
	v_fmac_f32_e32 v7, v66, v201
	v_fmac_f32_e32 v4, v66, v202
	v_fmac_f32_e32 v5, v66, v203
	s_waitcnt lgkmcnt(0)
	v_fmac_f32_e32 v10, v67, v204
	v_fmac_f32_e32 v11, v67, v205
	v_fmac_f32_e32 v8, v67, v206
	v_fmac_f32_e32 v9, v67, v207
	v_fmac_f32_e32 v6, v67, v208
	v_fmac_f32_e32 v7, v67, v209
	v_fmac_f32_e32 v4, v67, v210
	v_fmac_f32_e32 v5, v67, v211
	s_waitcnt vmcnt(0)
	v_mov_b32_e32 v13, s12
	s_addk_i32 s12, 0x200
	ds_read_b128 v[84:87], v13
	ds_read_b128 v[88:91], v13 offset:16
	ds_read_b128 v[92:95], v13 offset:32
	ds_read_b128 v[96:99], v13 offset:48
	ds_read_b128 v[100:103], v13 offset:64
	ds_read_b128 v[104:107], v13 offset:80
	ds_read_b128 v[108:111], v13 offset:96
	ds_read_b128 v[112:115], v13 offset:112
	ds_read_b128 v[116:119], v13 offset:128
	ds_read_b128 v[120:123], v13 offset:144
	ds_read_b128 v[124:127], v13 offset:160
	ds_read_b128 v[128:131], v13 offset:176
	ds_read_b128 v[132:135], v13 offset:192
	ds_read_b128 v[136:139], v13 offset:208
	ds_read_b128 v[140:143], v13 offset:224
	ds_read_b128 v[144:147], v13 offset:240
	ds_read_b128 v[148:151], v13 offset:256
	ds_read_b128 v[152:155], v13 offset:272
	ds_read_b128 v[156:159], v13 offset:288
	ds_read_b128 v[160:163], v13 offset:304
	ds_read_b128 v[164:167], v13 offset:320
	ds_read_b128 v[168:171], v13 offset:336
	ds_read_b128 v[172:175], v13 offset:352
	ds_read_b128 v[176:179], v13 offset:368
	ds_read_b128 v[180:183], v13 offset:384
	ds_read_b128 v[184:187], v13 offset:400
	ds_read_b128 v[188:191], v13 offset:416
	ds_read_b128 v[192:195], v13 offset:432
	ds_read_b128 v[196:199], v13 offset:448
	ds_read_b128 v[200:203], v13 offset:464
	ds_read_b128 v[204:207], v13 offset:480
	ds_read_b128 v[208:211], v13 offset:496
	s_waitcnt lgkmcnt(15)
	v_fmac_f32_e32 v10, v68, v84
	v_fmac_f32_e32 v11, v68, v85
	v_fmac_f32_e32 v8, v68, v86
	v_fmac_f32_e32 v9, v68, v87
	v_fmac_f32_e32 v6, v68, v88
	v_fmac_f32_e32 v7, v68, v89
	v_fmac_f32_e32 v4, v68, v90
	v_fmac_f32_e32 v5, v68, v91
	s_waitcnt lgkmcnt(15)
	v_fmac_f32_e32 v10, v69, v92
	v_fmac_f32_e32 v11, v69, v93
	v_fmac_f32_e32 v8, v69, v94
	v_fmac_f32_e32 v9, v69, v95
	v_fmac_f32_e32 v6, v69, v96
	v_fmac_f32_e32 v7, v69, v97
	v_fmac_f32_e32 v4, v69, v98
	v_fmac_f32_e32 v5, v69, v99
	s_waitcnt lgkmcnt(15)
	v_fmac_f32_e32 v10, v70, v100
	v_fmac_f32_e32 v11, v70, v101
	v_fmac_f32_e32 v8, v70, v102
	v_fmac_f32_e32 v9, v70, v103
	v_fmac_f32_e32 v6, v70, v104
	v_fmac_f32_e32 v7, v70, v105
	v_fmac_f32_e32 v4, v70, v106
	v_fmac_f32_e32 v5, v70, v107
	s_waitcnt lgkmcnt(15)
	v_fmac_f32_e32 v10, v71, v108
	v_fmac_f32_e32 v11, v71, v109
	v_fmac_f32_e32 v8, v71, v110
	v_fmac_f32_e32 v9, v71, v111
	v_fmac_f32_e32 v6, v71, v112
	v_fmac_f32_e32 v7, v71, v113
	v_fmac_f32_e32 v4, v71, v114
	v_fmac_f32_e32 v5, v71, v115
	s_waitcnt lgkmcnt(15)
	v_fmac_f32_e32 v10, v72, v116
	v_fmac_f32_e32 v11, v72, v117
	v_fmac_f32_e32 v8, v72, v118
	v_fmac_f32_e32 v9, v72, v119
	v_fmac_f32_e32 v6, v72, v120
	v_fmac_f32_e32 v7, v72, v121
	v_fmac_f32_e32 v4, v72, v122
	v_fmac_f32_e32 v5, v72, v123
	s_waitcnt lgkmcnt(15)
	v_fmac_f32_e32 v10, v73, v124
	v_fmac_f32_e32 v11, v73, v125
	v_fmac_f32_e32 v8, v73, v126
	v_fmac_f32_e32 v9, v73, v127
	v_fmac_f32_e32 v6, v73, v128
	v_fmac_f32_e32 v7, v73, v129
	v_fmac_f32_e32 v4, v73, v130
	v_fmac_f32_e32 v5, v73, v131
	s_waitcnt lgkmcnt(15)
	v_fmac_f32_e32 v10, v74, v132
	v_fmac_f32_e32 v11, v74, v133
	v_fmac_f32_e32 v8, v74, v134
	v_fmac_f32_e32 v9, v74, v135
	v_fmac_f32_e32 v6, v74, v136
	v_fmac_f32_e32 v7, v74, v137
	v_fmac_f32_e32 v4, v74, v138
	v_fmac_f32_e32 v5, v74, v139
	s_waitcnt lgkmcnt(15)
; #define LAS __attribute__((address_space(3)))
; __device__ __forceinline__ void phase_prologue(const In& in, unsigned char* ws, LAS unsigned char* lds, int tid, int wave, int lane) {
;     ...
;                 for (int j = 0; j < 16; ++j) { const f32x4 c0 = *(const LAS f32x4*)(condT + (k0 + j) * 8), c1 = *(const LAS f32x4*)(condT + (k0 + j) * 8 + 4);
;                     acc[0] += c0[0] * w[j]; acc[1] += c0[1] * w[j]; acc[2] += c0[2] * w[j]; acc[3] += c0[3] * w[j];
;                     acc[4] += c1[0] * w[j]; acc[5] += c1[1] * w[j]; acc[6] += c1[2] * w[j]; acc[7] += c1[3] * w[j]; }
;             }
;             const float bb = in.b_ada[(size_t)l * NMOD + col];
; #pragma unroll
;             for (int b = 0; b < 8; ++b) mod[((size_t)l * 8 + b) * NMOD + col] = acc[b] + bb;
	v_fmac_f32_e32 v10, v75, v140
	v_fmac_f32_e32 v11, v75, v141
	v_fmac_f32_e32 v8, v75, v142
	v_fmac_f32_e32 v9, v75, v143
	v_fmac_f32_e32 v6, v75, v144
	v_fmac_f32_e32 v7, v75, v145
	v_fmac_f32_e32 v4, v75, v146
	v_fmac_f32_e32 v5, v75, v147
	s_waitcnt lgkmcnt(14)
	v_fmac_f32_e32 v10, v76, v148
	v_fmac_f32_e32 v11, v76, v149
	v_fmac_f32_e32 v8, v76, v150
	v_fmac_f32_e32 v9, v76, v151
	v_fmac_f32_e32 v6, v76, v152
	v_fmac_f32_e32 v7, v76, v153
	v_fmac_f32_e32 v4, v76, v154
	v_fmac_f32_e32 v5, v76, v155
	s_waitcnt lgkmcnt(12)
	v_fmac_f32_e32 v10, v77, v156
	v_fmac_f32_e32 v11, v77, v157
	v_fmac_f32_e32 v8, v77, v158
	v_fmac_f32_e32 v9, v77, v159
	v_fmac_f32_e32 v6, v77, v160
	v_fmac_f32_e32 v7, v77, v161
	v_fmac_f32_e32 v4, v77, v162
	v_fmac_f32_e32 v5, v77, v163
	s_waitcnt lgkmcnt(10)
	v_fmac_f32_e32 v10, v78, v164
	v_fmac_f32_e32 v11, v78, v165
	v_fmac_f32_e32 v8, v78, v166
	v_fmac_f32_e32 v9, v78, v167
	v_fmac_f32_e32 v6, v78, v168
	v_fmac_f32_e32 v7, v78, v169
	v_fmac_f32_e32 v4, v78, v170
	v_fmac_f32_e32 v5, v78, v171
	s_waitcnt lgkmcnt(8)
	v_fmac_f32_e32 v10, v79, v172
	v_fmac_f32_e32 v11, v79, v173
	v_fmac_f32_e32 v8, v79, v174
	v_fmac_f32_e32 v9, v79, v175
	v_fmac_f32_e32 v6, v79, v176
	v_fmac_f32_e32 v7, v79, v177
	v_fmac_f32_e32 v4, v79, v178
	v_fmac_f32_e32 v5, v79, v179
	s_waitcnt lgkmcnt(6)
	v_fmac_f32_e32 v10, v80, v180
	v_fmac_f32_e32 v11, v80, v181
	v_fmac_f32_e32 v8, v80, v182
	v_fmac_f32_e32 v9, v80, v183
	v_fmac_f32_e32 v6, v80, v184
	v_fmac_f32_e32 v7, v80, v185
	v_fmac_f32_e32 v4, v80, v186
	v_fmac_f32_e32 v5, v80, v187
	s_waitcnt lgkmcnt(4)
	v_fmac_f32_e32 v10, v81, v188
	v_fmac_f32_e32 v11, v81, v189
	v_fmac_f32_e32 v8, v81, v190
	v_fmac_f32_e32 v9, v81, v191
	v_fmac_f32_e32 v6, v81, v192
	v_fmac_f32_e32 v7, v81, v193
	v_fmac_f32_e32 v4, v81, v194
	v_fmac_f32_e32 v5, v81, v195
	s_waitcnt lgkmcnt(2)
	v_fmac_f32_e32 v10, v82, v196
	v_fmac_f32_e32 v11, v82, v197
	v_fmac_f32_e32 v8, v82, v198
	v_fmac_f32_e32 v9, v82, v199
	v_fmac_f32_e32 v6, v82, v200
	v_fmac_f32_e32 v7, v82, v201
	v_fmac_f32_e32 v4, v82, v202
	v_fmac_f32_e32 v5, v82, v203
	s_waitcnt lgkmcnt(0)
	v_fmac_f32_e32 v10, v83, v204
	v_fmac_f32_e32 v11, v83, v205
	v_fmac_f32_e32 v8, v83, v206
	v_fmac_f32_e32 v9, v83, v207
	v_fmac_f32_e32 v6, v83, v208
	v_fmac_f32_e32 v7, v83, v209
	v_fmac_f32_e32 v4, v83, v210
	v_fmac_f32_e32 v5, v83, v211
	s_mul_i32 s0, s9, 0x120
	v_readlane_b32 s36, v252, 19
	s_sub_i32 s0, s10, s0
	v_readlane_b32 s42, v252, 25
	v_readlane_b32 s43, v252, 26
	v_lshl_or_b32 v2, s0, 6, v16
	s_mul_i32 s0, s9, 0x12000
	s_mov_b64 s[10:11], s[42:43]
	v_ashrrev_i32_e32 v3, 31, v2
	s_mul_hi_i32 s1, s9, 0x12000
	s_add_u32 s0, s10, s0
	s_addc_u32 s1, s11, s1
	v_lshlrev_b64 v[2:3], 2, v[2:3]
	v_lshl_add_u64 v[12:13], s[0:1], 0, v[2:3]
	global_load_dword v17, v[12:13], off
	v_readlane_b32 s0, v252, 51
	v_readlane_b32 s1, v252, 52
	v_mov_b32_e32 v12, 0x90000
	s_mov_b32 s4, 0x12000
	v_lshl_add_u64 v[2:3], s[0:1], 0, v[2:3]
	v_mad_i64_i32 v[2:3], s[0:1], s9, v12, v[2:3]
	v_add_co_u32_e32 v12, vcc, s4, v2
	s_mov_b32 s5, 0x24000
	s_nop 0
	v_addc_co_u32_e32 v13, vcc, 0, v3, vcc
	v_add_co_u32_e32 v14, vcc, s5, v2
	s_mov_b32 s6, 0x36000
	s_nop 0
	v_addc_co_u32_e32 v15, vcc, 0, v3, vcc
	v_add_co_u32_e32 v18, vcc, s6, v2
	s_mov_b32 s7, 0x48000
	s_nop 0
	v_addc_co_u32_e32 v19, vcc, 0, v3, vcc
	v_add_co_u32_e32 v20, vcc, s7, v2
	s_mov_b32 s10, 0x5a000
	s_nop 0
	v_addc_co_u32_e32 v21, vcc, 0, v3, vcc
	v_add_co_u32_e32 v22, vcc, s10, v2
	v_readlane_b32 s37, v252, 20
	s_nop 0
	v_addc_co_u32_e32 v23, vcc, 0, v3, vcc
	v_add_co_u32_e32 v24, vcc, 0x6c000, v2
	v_readlane_b32 s38, v252, 21
	s_nop 0
	v_addc_co_u32_e32 v25, vcc, 0, v3, vcc
	v_add_co_u32_e32 v26, vcc, 0x7e000, v2
	v_readlane_b32 s39, v252, 22
	v_readlane_b32 s40, v252, 23
	v_readlane_b32 s41, v252, 24
	v_readlane_b32 s44, v252, 27
	v_readlane_b32 s45, v252, 28
	v_readlane_b32 s46, v252, 29
	v_readlane_b32 s47, v252, 30
	v_readlane_b32 s48, v252, 31
	v_readlane_b32 s49, v252, 32
	v_readlane_b32 s50, v252, 33
	v_readlane_b32 s51, v252, 34
	v_addc_co_u32_e32 v27, vcc, 0, v3, vcc
	s_waitcnt vmcnt(0)
	v_add_f32_e32 v10, v10, v17
	v_add_f32_e32 v11, v11, v17
	v_add_f32_e32 v8, v8, v17
	v_add_f32_e32 v9, v9, v17
	v_add_f32_e32 v6, v6, v17
	v_add_f32_e32 v7, v7, v17
	v_add_f32_e32 v4, v4, v17
	v_add_f32_e32 v5, v5, v17
	global_store_dword v[2:3], v10, off
	global_store_dword v[12:13], v11, off
	global_store_dword v[14:15], v8, off
	global_store_dword v[18:19], v9, off
	global_store_dword v[20:21], v6, off
	global_store_dword v[22:23], v7, off
	global_store_dword v[24:25], v4, off
	global_store_dword v[26:27], v5, off

; __device__ __forceinline__ unsigned cvt_pk_bf16(float lo, float hi) { unsigned r; asm volatile("v_cvt_pk_bf16_f32 %0, %1, %2" : "=v"(r) : "v"(lo), "v"(hi)); return r; }
; __device__ __forceinline__ float bflo(unsigned w) { return __uint_as_float(w << 16); }
; __device__ __forceinline__ float bfhi(unsigned w) { return __uint_as_float(w & 0xffff0000u); }
; __device__ __forceinline__ float fast_rcp(float x) { return __builtin_amdgcn_rcpf(x); }
; __device__ __forceinline__ float fast_exp2(float x) { return __builtin_amdgcn_exp2f(x); }
; __device__ __forceinline__ void st_wt32(void* p, unsigned v) { __hip_atomic_store((unsigned*)p, v, __ATOMIC_RELAXED, __HIP_MEMORY_SCOPE_AGENT); }
; __device__ __forceinline__ void phase_pre(bf16* UB, bf16* UC, const ScanBufs sb, int layer, const float* lb_logits, const float* gla_b, int it0, int it_end, int it_step, int lane) {
;     ...
;             for (int e = 0; e < 2; ++e) {
;                 float P = 1.0f;
; #pragma unroll
;                 for (int i = 0; i < 16; ++i) {
;                     const float qv = e ? bfhi(qw[i]) : bflo(qw[i]), zv = e ? bfhi(fw[i]) : bflo(fw[i]);
;                     float ff, kf;
;                     if (type == 0) {
;                         const float en = fast_exp2(-fabsf(zv) * LOG2E);
;                         const float sp = fast_rcp(1.0f + en), sn = en * sp;
;                         const float s1 = zv >= 0.f ? sp : sn, s0 = zv >= 0.f ? sn : sp;
;                         kf = (1.0f - par[e]) * s0; ff = par[e] + (1.0f - par[e]) * s1; qo[e][i] = qv;
;                     } else {
;                         const float xg = zv + par[e];
;                         const float lsg = fminf(xg, 0.f) - __logf(1.0f + fast_exp2(-fabsf(xg) * LOG2E));
;                         ff = fast_exp2(lsg * (LOG2E / 16.0f)); kf = e ? bfhi(kw[i]) : bflo(kw[i]); qo[e][i] = qv * 0.08838834764831845f;
;                     }
;                     P *= ff;
;                     qo[e][i] *= P; po[e][i] = kf * fminf(fast_rcp(P), 5.5e34f);
;                 }
;                 Dv[e] = P;
;             }
; #pragma unroll
;             for (int i = 0; i < 16; ++i) { st_wt32(qp + (size_t)i * ld, cvt_pk_bf16(qo[0][i], qo[1][i])); st_wt32(kp + (size_t)i * ld, cvt_pk_bf16(po[0][i], po[1][i])); }
.LBB0_584:
	v_mul_f32_e32 v124, v128, v134
	v_mul_f32_e32 v130, v124, v130
	v_mul_f32_e32 v134, v130, v136
	v_mul_f32_e32 v122, v134, v122
	v_mul_f32_e32 v116, v122, v116
	v_mul_f32_e32 v111, v116, v111
	v_mul_f32_e32 v106, v111, v106
	v_mul_f32_e32 v100, v106, v100
	v_mul_f32_e32 v96, v100, v96
	v_mul_f32_e32 v91, v96, v91
	v_mul_f32_e32 v85, v91, v85
	v_mul_f32_e32 v81, v85, v81
	v_mul_f32_e32 v135, v81, v75
	v_mul_f32_e32 v75, v135, v72
	v_rcp_f32_e32 v60, v75
	v_mul_f32_e32 v72, v78, v81
	v_rcp_f32_e32 v78, v85
	v_mul_f32_e32 v49, v67, v75
	v_min_f32_e32 v60, 0x79297b5a, v60
	v_mul_f32_e32 v60, v71, v60
	v_rcp_f32_e32 v71, v135
	v_min_f32_e32 v78, 0x79297b5a, v78
	v_mul_f32_e32 v78, v84, v78
	v_rcp_f32_e32 v84, v96
	v_min_f32_e32 v71, 0x79297b5a, v71
	v_mul_f32_e32 v71, v74, v71
	v_mul_f32_e32 v74, v83, v85
	v_mul_f32_e32 v83, v92, v96
	v_mul_f32_e32 v85, v98, v100
	v_mul_f32_e32 v96, v113, v116
	v_rcp_f32_e32 v98, v116
	v_mul_f32_e32 v116, v37, v48
	v_mul_f32_e32 v67, v73, v135
	v_rcp_f32_e32 v73, v81
	v_mul_f32_e32 v52, v116, v52
	v_mul_f32_e32 v54, v52, v54
	v_mul_f32_e32 v43, v43, v52
	v_rcp_f32_e32 v52, v52
	v_min_f32_e32 v98, 0x79297b5a, v98
	v_min_f32_e32 v73, 0x79297b5a, v73
	v_min_f32_e32 v84, 0x79297b5a, v84
	v_mul_f32_e32 v98, v114, v98
	v_rcp_f32_e32 v114, v128
	v_mul_f32_e32 v39, v39, v37
	v_rcp_f32_e32 v37, v37
	v_mul_f32_e32 v73, v80, v73
	v_mul_f32_e32 v80, v88, v91
	v_rcp_f32_e32 v81, v91
	v_mul_f32_e32 v84, v94, v84
	v_rcp_f32_e32 v91, v106
	v_rcp_f32_e32 v94, v111
	v_min_f32_e32 v52, 0x79297b5a, v52
	v_mul_f32_e32 v92, v107, v111
	v_rcp_f32_e32 v111, v124
	v_mul_f32_e32 v42, v42, v52
	v_rcp_f32_e32 v52, v116
	v_rcp_f32_e32 v107, v130
	v_min_f32_e32 v114, 0x79297b5a, v114
	v_min_f32_e32 v37, 0x79297b5a, v37
	v_min_f32_e32 v91, 0x79297b5a, v91
	v_min_f32_e32 v94, 0x79297b5a, v94
	v_mul_f32_e32 v113, v131, v128
	v_mul_f32_e32 v114, v127, v114
	v_mul_f32_e32 v36, v36, v37
	v_cvt_pk_bf16_f32 v39, v39, v113
	v_mov_b64_e32 v[232:233], v[2:3]
	v_mov_b32_e32 v236, s57
	v_lshlrev_b32_e32 v236, 13, v236
	v_lshl_add_u32 v237, v187, 4, v236
	v_lshl_add_u32 v236, v187, 2, v236
	ds_write_b32 v236, v39
	v_cvt_pk_bf16_f32 v2, v36, v114
	v_mul_f32_e32 v91, v105, v91
	v_mul_f32_e32 v94, v109, v94
	v_rcp_f32_e32 v105, v134
	v_mul_f32_e32 v109, v132, v124
	v_min_f32_e32 v111, 0x79297b5a, v111
	v_mul_f32_e32 v56, v54, v56
	v_mul_f32_e32 v44, v44, v54
	v_rcp_f32_e32 v54, v54
	v_mul_f32_e32 v40, v40, v116
	v_min_f32_e32 v52, 0x79297b5a, v52
	v_mov_b64_e32 v[234:235], v[4:5]
	ds_write_b32 v236, v2 offset:4096
	v_cvt_pk_bf16_f32 v2, v40, v109
	v_min_f32_e32 v81, 0x79297b5a, v81
	v_rcp_f32_e32 v88, v100
	v_mul_f32_e32 v111, v133, v111
	v_mul_f32_e32 v41, v41, v52
	ds_write_b32 v236, v2 offset:256
	v_lshl_add_u64 v[2:3], v[4:5], 0, s[60:61]
	v_cvt_pk_bf16_f32 v4, v41, v111
	v_mul_f32_e32 v81, v90, v81
	v_mul_f32_e32 v90, v102, v106
	v_rcp_f32_e32 v100, v122
	v_mul_f32_e32 v106, v126, v130
	v_min_f32_e32 v107, 0x79297b5a, v107
	v_mul_f32_e32 v59, v56, v59
	v_mul_f32_e32 v47, v47, v56
	v_rcp_f32_e32 v56, v56
	ds_write_b32 v236, v4 offset:4352
	v_cvt_pk_bf16_f32 v4, v43, v106
	v_mul_f32_e32 v107, v129, v107
	ds_write_b32 v236, v4 offset:512
	v_lshl_add_u64 v[2:3], v[2:3], 0, s[60:61]
	v_cvt_pk_bf16_f32 v4, v42, v107
	v_mul_f32_e32 v102, v123, v134
	v_min_f32_e32 v105, 0x79297b5a, v105
	v_mul_f32_e32 v64, v59, v64
	v_mul_f32_e32 v50, v50, v59
	v_rcp_f32_e32 v59, v59
	v_min_f32_e32 v54, 0x79297b5a, v54
	ds_write_b32 v236, v4 offset:4608
	v_cvt_pk_bf16_f32 v4, v44, v102
	v_min_f32_e32 v88, 0x79297b5a, v88
	v_mul_f32_e32 v105, v125, v105
	v_mul_f32_e32 v45, v45, v54
	ds_write_b32 v236, v4 offset:768
	v_lshl_add_u64 v[2:3], v[2:3], 0, s[60:61]
	v_cvt_pk_bf16_f32 v4, v45, v105
	v_mul_f32_e32 v88, v99, v88
	v_mul_f32_e32 v99, v117, v122
	v_min_f32_e32 v100, 0x79297b5a, v100
	v_mul_f32_e32 v69, v64, v69
	v_mul_f32_e32 v55, v55, v64
	v_rcp_f32_e32 v64, v64
	v_min_f32_e32 v56, 0x79297b5a, v56
	ds_write_b32 v236, v4 offset:4864
	v_cvt_pk_bf16_f32 v4, v47, v99
	v_mul_f32_e32 v100, v120, v100
	v_mul_f32_e32 v46, v46, v56
	ds_write_b32 v236, v4 offset:1024
	v_lshl_add_u64 v[2:3], v[2:3], 0, s[60:61]
	v_cvt_pk_bf16_f32 v4, v46, v100
	v_mul_f32_e32 v76, v69, v76
	v_mul_f32_e32 v57, v57, v69
	v_rcp_f32_e32 v69, v69
	v_min_f32_e32 v59, 0x79297b5a, v59
	ds_write_b32 v236, v4 offset:5120
	v_cvt_pk_bf16_f32 v4, v50, v96
	v_mul_f32_e32 v51, v51, v59
	ds_write_b32 v236, v4 offset:1280
	v_lshl_add_u64 v[2:3], v[2:3], 0, s[60:61]
	v_cvt_pk_bf16_f32 v4, v51, v98
	v_mul_f32_e32 v82, v76, v82
	v_mul_f32_e32 v62, v62, v76
	v_rcp_f32_e32 v76, v76
	v_min_f32_e32 v64, 0x79297b5a, v64
	ds_write_b32 v236, v4 offset:5376
	v_cvt_pk_bf16_f32 v4, v55, v92
	v_mul_f32_e32 v53, v53, v64
	ds_write_b32 v236, v4 offset:1536
	v_lshl_add_u64 v[2:3], v[2:3], 0, s[60:61]
	v_cvt_pk_bf16_f32 v4, v53, v94
	v_mul_f32_e32 v89, v82, v89
	v_mul_f32_e32 v68, v68, v82
	v_rcp_f32_e32 v82, v82
	v_min_f32_e32 v69, 0x79297b5a, v69
	ds_write_b32 v236, v4 offset:5632
	v_cvt_pk_bf16_f32 v4, v57, v90
	v_mul_f32_e32 v58, v58, v69
; __device__ __forceinline__ unsigned cvt_pk_bf16(float lo, float hi) { unsigned r; asm volatile("v_cvt_pk_bf16_f32 %0, %1, %2" : "=v"(r) : "v"(lo), "v"(hi)); return r; }
; __device__ __forceinline__ void st_wt32(void* p, unsigned v) { __hip_atomic_store((unsigned*)p, v, __ATOMIC_RELAXED, __HIP_MEMORY_SCOPE_AGENT); }
; __device__ __forceinline__ void phase_pre(bf16* UB, bf16* UC, const ScanBufs sb, int layer, const float* lb_logits, const float* gla_b, int it0, int it_end, int it_step, int lane) {
;     ...
;             for (int i = 0; i < 16; ++i) { st_wt32(qp + (size_t)i * ld, cvt_pk_bf16(qo[0][i], qo[1][i])); st_wt32(kp + (size_t)i * ld, cvt_pk_bf16(po[0][i], po[1][i])); }
;             float* dp = (type == 0 ? sb.DB : sb.DC) + (size_t)ck * nch + ch;
;             st_wt32(dp, __float_as_uint(Dv[0])); st_wt32(dp + 1, __float_as_uint(Dv[1]));
	ds_write_b32 v236, v4 offset:1792
	v_lshl_add_u64 v[2:3], v[2:3], 0, s[60:61]
	v_cvt_pk_bf16_f32 v4, v58, v91
	v_mul_f32_e32 v95, v89, v95
	v_mul_f32_e32 v79, v79, v89
	v_rcp_f32_e32 v89, v89
	v_min_f32_e32 v76, 0x79297b5a, v76
	ds_write_b32 v236, v4 offset:5888
	v_cvt_pk_bf16_f32 v4, v62, v85
	v_mul_f32_e32 v61, v61, v76
	ds_write_b32 v236, v4 offset:2048
	v_lshl_add_u64 v[2:3], v[2:3], 0, s[60:61]
	v_cvt_pk_bf16_f32 v4, v61, v88
	v_mul_f32_e32 v101, v95, v101
	v_mul_f32_e32 v86, v86, v95
	v_rcp_f32_e32 v95, v95
	v_min_f32_e32 v82, 0x79297b5a, v82
	ds_write_b32 v236, v4 offset:6144
	v_cvt_pk_bf16_f32 v4, v68, v83
	v_mul_f32_e32 v70, v70, v82
	ds_write_b32 v236, v4 offset:2304
	v_lshl_add_u64 v[2:3], v[2:3], 0, s[60:61]
	v_cvt_pk_bf16_f32 v4, v70, v84
	v_mul_f32_e32 v108, v101, v108
	v_mul_f32_e32 v97, v97, v101
	v_rcp_f32_e32 v101, v101
	v_min_f32_e32 v89, 0x79297b5a, v89
	ds_write_b32 v236, v4 offset:6400
	v_cvt_pk_bf16_f32 v4, v79, v80
	v_mul_f32_e32 v77, v77, v89
	ds_write_b32 v236, v4 offset:2560
	v_lshl_add_u64 v[2:3], v[2:3], 0, s[60:61]
	v_cvt_pk_bf16_f32 v4, v77, v81
	v_mul_f32_e32 v115, v108, v115
	v_mul_f32_e32 v103, v103, v108
	v_rcp_f32_e32 v108, v108
	v_min_f32_e32 v95, 0x79297b5a, v95
	v_readlane_b32 s16, v252, 11
	ds_write_b32 v236, v4 offset:6656
	v_cvt_pk_bf16_f32 v4, v86, v74
	s_ashr_i32 s13, s12, 31
	v_mul_f32_e32 v87, v87, v95
	v_readlane_b32 s18, v252, 13
	ds_write_b32 v236, v4 offset:2816
	v_lshl_add_u64 v[2:3], v[2:3], 0, s[60:61]
	v_cvt_pk_bf16_f32 v4, v87, v78
	v_mul_f32_e32 v48, v115, v121
	v_mul_f32_e32 v112, v112, v115
	v_rcp_f32_e32 v115, v115
	v_min_f32_e32 v101, 0x79297b5a, v101
	v_readlane_b32 s19, v252, 14
	s_add_u32 s10, s18, s42
	ds_write_b32 v236, v4 offset:6912
	v_cvt_pk_bf16_f32 v4, v97, v72
	v_mul_f32_e32 v93, v93, v101
	s_addc_u32 s11, s19, s43
	v_mul_f32_e32 v37, v75, v65
	ds_write_b32 v236, v4 offset:3072
	v_lshl_add_u64 v[2:3], v[2:3], 0, s[60:61]
	v_cvt_pk_bf16_f32 v4, v93, v73
	s_lshl_b64 s[0:1], s[12:13], s36
	v_mul_f32_e32 v117, v118, v48
	v_rcp_f32_e32 v118, v48
	v_min_f32_e32 v108, 0x79297b5a, v108
	v_rcp_f32_e32 v54, v37
	ds_write_b32 v236, v4 offset:7168
	v_cvt_pk_bf16_f32 v4, v103, v67
	s_lshl_b64 s[0:1], s[0:1], 2
	v_mul_f32_e32 v104, v104, v108
	ds_write_b32 v236, v4 offset:3328
	v_lshl_add_u64 v[2:3], v[2:3], 0, s[60:61]
	v_cvt_pk_bf16_f32 v4, v104, v71
	s_add_u32 s0, s10, s0
	v_min_f32_e32 v115, 0x79297b5a, v115
	ds_write_b32 v236, v4 offset:7424
	v_cvt_pk_bf16_f32 v4, v112, v49
	s_addc_u32 s1, s11, s1
	v_mul_f32_e32 v110, v110, v115
	ds_write_b32 v236, v4 offset:3584
	v_lshl_add_u64 v[2:3], v[2:3], 0, s[60:61]
	v_cvt_pk_bf16_f32 v4, v110, v60
	v_lshl_add_u64 v[0:1], v[0:1], 2, s[0:1]
	s_add_i32 s0, s7, 8
	s_addk_i32 s27, 0x400
	v_min_f32_e32 v118, 0x79297b5a, v118
	v_mul_f32_e32 v52, v63, v37
	v_min_f32_e32 v54, 0x79297b5a, v54
	ds_write_b32 v236, v4 offset:7680
	v_cvt_pk_bf16_f32 v4, v117, v52
	v_lshl_add_u64 v[2:3], v[2:3], 0, s[60:61]
	s_cmp_lt_i32 s7, s6
	s_mov_b32 s7, s0
	v_mul_f32_e32 v118, v119, v118
	v_readlane_b32 s17, v252, 12
	v_readlane_b32 s20, v252, 15
	v_readlane_b32 s21, v252, 16
	v_readlane_b32 s22, v252, 17
	v_readlane_b32 s23, v252, 18
	v_mul_f32_e32 v54, v66, v54
	ds_write_b32 v236, v4 offset:3840
	v_cvt_pk_bf16_f32 v4, v118, v54
	ds_write_b32 v236, v4 offset:7936
	global_store_dword v[0:1], v48, off sc1
	global_store_dword v[0:1], v37, off offset:4 sc1
	v_lshrrev_b32_e32 v238, 4, v187
	v_mul_lo_u32 v238, v238, s60
	v_and_b32_e32 v239, 15, v187
	v_lshl_add_u32 v238, v239, 4, v238
	v_lshlrev_b32_e32 v239, 2, v187
	v_sub_u32_e32 v238, v238, v239
	v_mov_b32_e32 v239, 0
	v_lshl_add_u64 v[232:233], v[232:233], 0, v[238:239]
	v_lshl_add_u64 v[234:235], v[234:235], 0, v[238:239]
	v_mov_b32_e32 v238, s60
	v_lshlrev_b32_e32 v238, 2, v238
	ds_read_b128 v[240:243], v237
	ds_read_b128 v[244:247], v237 offset:4096
	ds_read_b128 v[140:143], v237 offset:1024
	ds_read_b128 v[144:147], v237 offset:5120
	ds_read_b128 v[148:151], v237 offset:2048
	ds_read_b128 v[152:155], v237 offset:6144
	ds_read_b128 v[156:159], v237 offset:3072
	ds_read_b128 v[160:163], v237 offset:7168
	s_waitcnt lgkmcnt(7)
	global_store_dwordx4 v[232:233], v[240:243], off sc1
	s_waitcnt lgkmcnt(6)
	global_store_dwordx4 v[234:235], v[244:247], off sc1
	v_lshl_add_u64 v[232:233], v[232:233], 0, v[238:239]
	v_lshl_add_u64 v[234:235], v[234:235], 0, v[238:239]
	s_waitcnt lgkmcnt(5)
	global_store_dwordx4 v[232:233], v[140:143], off sc1
	s_waitcnt lgkmcnt(4)
	global_store_dwordx4 v[234:235], v[144:147], off sc1
	v_lshl_add_u64 v[232:233], v[232:233], 0, v[238:239]
	v_lshl_add_u64 v[234:235], v[234:235], 0, v[238:239]
	s_waitcnt lgkmcnt(3)
	global_store_dwordx4 v[232:233], v[148:151], off sc1
	s_waitcnt lgkmcnt(2)
	global_store_dwordx4 v[234:235], v[152:155], off sc1
	v_lshl_add_u64 v[232:233], v[232:233], 0, v[238:239]
	v_lshl_add_u64 v[234:235], v[234:235], 0, v[238:239]
	s_waitcnt lgkmcnt(1)
	global_store_dwordx4 v[232:233], v[156:159], off sc1
	s_waitcnt lgkmcnt(0)
	global_store_dwordx4 v[234:235], v[160:163], off sc1
	s_cbranch_scc0 .LBB0_757
